# GEMM K-loops: loop-control SALU work moved in front of the loop-back barrier (back-edge rotation), exit path gets its own barrier copy
# baseline (speedup 1.0000x reference)
.LBB0_224:
	s_or_b32 s26, s79, 1
	ds_read_b128 v[144:147], v153
	ds_read_b128 v[170:173], v154
	ds_read_b128 v[176:179], v155
	ds_read_b128 v[180:183], v156
	ds_read_b128 v[184:187], v157
	ds_read_b128 v[188:191], v158
	ds_read_b128 v[192:195], v159
	ds_read_b128 v[196:199], v160
	s_lshl_b64 s[50:51], s[26:27], 7
	s_add_u32 s52, s28, s50
	s_addc_u32 s53, s29, s51
	s_add_i32 s26, s79, 2
	s_lshl_b64 s[56:57], s[26:27], 7
	s_add_u32 s58, s28, s56
	s_addc_u32 s59, s29, s57
	s_and_b64 s[50:51], s[48:49], exec
	s_cselect_b32 s51, s59, s11
	s_cselect_b32 s50, s58, s15
	s_add_u32 s56, s30, s56
	s_addc_u32 s57, s31, s57
	s_and_b64 s[48:49], s[48:49], exec
	s_cselect_b32 s49, s57, s35
	s_cselect_b32 s48, s56, s37
	s_mov_b32 m0, s72
	v_lshl_add_u64 v[232:233], s[52:53], 0, v[128:129]
	ds_read_b128 v[200:203], v151
	ds_read_b128 v[204:207], v151 offset:1024
	ds_read_b128 v[208:211], v151 offset:2048
	ds_read_b128 v[212:215], v151 offset:3072
	ds_read_b128 v[216:219], v151 offset:4096
	ds_read_b128 v[220:223], v151 offset:5120
	ds_read_b128 v[224:227], v151 offset:6144
	ds_read_b128 v[228:231], v151 offset:7168
	global_load_lds_dwordx4 v[232:233], off
	v_lshl_add_u64 v[232:233], s[52:53], 0, v[130:131]
	s_mov_b32 m0, s73
	s_nop 0
	global_load_lds_dwordx4 v[232:233], off
	v_lshl_add_u64 v[232:233], s[52:53], 0, v[132:133]
	s_mov_b32 m0, s74
	s_nop 0
	global_load_lds_dwordx4 v[232:233], off
	v_lshl_add_u64 v[232:233], s[52:53], 0, v[134:135]
	s_mov_b32 m0, s75
	s_nop 0
	global_load_lds_dwordx4 v[232:233], off
	s_waitcnt lgkmcnt(8)
	s_barrier
	s_waitcnt lgkmcnt(0)
	s_setprio 1
	s_waitcnt lgkmcnt(0)
	v_mfma_f32_16x16x32_bf16 v[124:127], v[144:147], v[200:203], v[124:127]
	v_mfma_f32_16x16x32_bf16 v[120:123], v[176:179], v[200:203], v[120:123]
	v_mfma_f32_16x16x32_bf16 v[116:119], v[144:147], v[208:211], v[116:119]
	v_mfma_f32_16x16x32_bf16 v[108:111], v[176:179], v[208:211], v[108:111]
	v_mfma_f32_16x16x32_bf16 v[100:103], v[144:147], v[216:219], v[100:103]
	v_mfma_f32_16x16x32_bf16 v[92:95], v[176:179], v[216:219], v[92:95]
	v_mfma_f32_16x16x32_bf16 v[84:87], v[144:147], v[224:227], v[84:87]
	v_mfma_f32_16x16x32_bf16 v[76:79], v[176:179], v[224:227], v[76:79]
	v_mfma_f32_16x16x32_bf16 v[124:127], v[170:173], v[204:207], v[124:127]
	v_mfma_f32_16x16x32_bf16 v[120:123], v[180:183], v[204:207], v[120:123]
	v_mfma_f32_16x16x32_bf16 v[116:119], v[170:173], v[212:215], v[116:119]
	v_mfma_f32_16x16x32_bf16 v[108:111], v[180:183], v[212:215], v[108:111]
	v_mfma_f32_16x16x32_bf16 v[100:103], v[170:173], v[220:223], v[100:103]
	v_mfma_f32_16x16x32_bf16 v[92:95], v[180:183], v[220:223], v[92:95]
	v_mfma_f32_16x16x32_bf16 v[84:87], v[170:173], v[228:231], v[84:87]
	v_mfma_f32_16x16x32_bf16 v[76:79], v[180:183], v[228:231], v[76:79]
	s_setprio 0
	s_setprio 1
	v_mfma_f32_16x16x32_bf16 v[112:115], v[184:187], v[200:203], v[112:115]
	v_mfma_f32_16x16x32_bf16 v[104:107], v[192:195], v[200:203], v[104:107]
	v_mfma_f32_16x16x32_bf16 v[96:99], v[184:187], v[208:211], v[96:99]
	v_mfma_f32_16x16x32_bf16 v[88:91], v[192:195], v[208:211], v[88:91]
	v_mfma_f32_16x16x32_bf16 v[80:83], v[184:187], v[216:219], v[80:83]
	v_mfma_f32_16x16x32_bf16 v[72:75], v[192:195], v[216:219], v[72:75]
	v_mfma_f32_16x16x32_bf16 v[68:71], v[184:187], v[224:227], v[68:71]
	v_mfma_f32_16x16x32_bf16 v[64:67], v[192:195], v[224:227], v[64:67]
	v_mfma_f32_16x16x32_bf16 v[112:115], v[188:191], v[204:207], v[112:115]
	v_mfma_f32_16x16x32_bf16 v[104:107], v[196:199], v[204:207], v[104:107]
	v_mfma_f32_16x16x32_bf16 v[96:99], v[188:191], v[212:215], v[96:99]
	v_mfma_f32_16x16x32_bf16 v[88:91], v[196:199], v[212:215], v[88:91]
	v_mfma_f32_16x16x32_bf16 v[80:83], v[188:191], v[220:223], v[80:83]
	v_mfma_f32_16x16x32_bf16 v[72:75], v[196:199], v[220:223], v[72:75]
	v_mfma_f32_16x16x32_bf16 v[68:71], v[188:191], v[228:231], v[68:71]
	v_mfma_f32_16x16x32_bf16 v[64:67], v[196:199], v[228:231], v[64:67]
	s_setprio 0
	s_barrier
	s_mov_b32 m0, s55
	v_lshl_add_u64 v[232:233], s[48:49], 0, v[136:137]
	s_add_u32 s52, s48, 0x40000
	ds_read_b128 v[200:203], v151 offset:16384
	ds_read_b128 v[204:207], v151 offset:17408
	ds_read_b128 v[208:211], v151 offset:18432
	ds_read_b128 v[212:215], v151 offset:19456
	ds_read_b128 v[216:219], v151 offset:20480
	ds_read_b128 v[220:223], v151 offset:21504
	ds_read_b128 v[224:227], v151 offset:22528
	ds_read_b128 v[228:231], v151 offset:23552
	global_load_lds_dwordx4 v[232:233], off
	v_lshl_add_u64 v[234:235], s[48:49], 0, v[138:139]
	s_mov_b32 m0, s60
	s_addc_u32 s53, s49, 0
	global_load_lds_dwordx4 v[234:235], off
	v_lshl_add_u64 v[236:237], s[52:53], 0, v[136:137]
	s_mov_b32 m0, s61
	s_nop 0
	global_load_lds_dwordx4 v[236:237], off
	v_lshl_add_u64 v[236:237], s[52:53], 0, v[138:139]
	s_mov_b32 m0, s62
	s_nop 0
	global_load_lds_dwordx4 v[236:237], off
	s_waitcnt vmcnt(4)
	s_waitcnt lgkmcnt(0)
	s_barrier
	s_setprio 1
	s_waitcnt lgkmcnt(0)
	v_mfma_f32_16x16x32_bf16 v[60:63], v[144:147], v[200:203], v[60:63]
	v_mfma_f32_16x16x32_bf16 v[56:59], v[176:179], v[200:203], v[56:59]
	v_mfma_f32_16x16x32_bf16 v[52:55], v[144:147], v[208:211], v[52:55]
	v_mfma_f32_16x16x32_bf16 v[44:47], v[176:179], v[208:211], v[44:47]
	v_mfma_f32_16x16x32_bf16 v[36:39], v[144:147], v[216:219], v[36:39]
	v_mfma_f32_16x16x32_bf16 v[28:31], v[176:179], v[216:219], v[28:31]
	v_mfma_f32_16x16x32_bf16 v[20:23], v[144:147], v[224:227], v[20:23]
	v_mfma_f32_16x16x32_bf16 v[12:15], v[176:179], v[224:227], v[12:15]
	v_mfma_f32_16x16x32_bf16 v[60:63], v[170:173], v[204:207], v[60:63]
	v_mfma_f32_16x16x32_bf16 v[56:59], v[180:183], v[204:207], v[56:59]
	v_mfma_f32_16x16x32_bf16 v[52:55], v[170:173], v[212:215], v[52:55]
	v_mfma_f32_16x16x32_bf16 v[44:47], v[180:183], v[212:215], v[44:47]
	v_mfma_f32_16x16x32_bf16 v[36:39], v[170:173], v[220:223], v[36:39]
	v_mfma_f32_16x16x32_bf16 v[28:31], v[180:183], v[220:223], v[28:31]
	v_mfma_f32_16x16x32_bf16 v[20:23], v[170:173], v[228:231], v[20:23]
	v_mfma_f32_16x16x32_bf16 v[12:15], v[180:183], v[228:231], v[12:15]
	s_setprio 0
	s_setprio 1
	v_mfma_f32_16x16x32_bf16 v[48:51], v[184:187], v[200:203], v[48:51]
	v_mfma_f32_16x16x32_bf16 v[40:43], v[192:195], v[200:203], v[40:43]
	v_mfma_f32_16x16x32_bf16 v[32:35], v[184:187], v[208:211], v[32:35]
	v_mfma_f32_16x16x32_bf16 v[24:27], v[192:195], v[208:211], v[24:27]
	v_mfma_f32_16x16x32_bf16 v[16:19], v[184:187], v[216:219], v[16:19]
	v_mfma_f32_16x16x32_bf16 v[8:11], v[192:195], v[216:219], v[8:11]
	v_mfma_f32_16x16x32_bf16 v[4:7], v[184:187], v[224:227], v[4:7]
	v_mfma_f32_16x16x32_bf16 v[0:3], v[192:195], v[224:227], v[0:3]
	v_mfma_f32_16x16x32_bf16 v[48:51], v[188:191], v[204:207], v[48:51]
	v_mfma_f32_16x16x32_bf16 v[40:43], v[196:199], v[204:207], v[40:43]
	v_mfma_f32_16x16x32_bf16 v[32:35], v[188:191], v[212:215], v[32:35]
	v_mfma_f32_16x16x32_bf16 v[24:27], v[196:199], v[212:215], v[24:27]
	v_mfma_f32_16x16x32_bf16 v[16:19], v[188:191], v[220:223], v[16:19]
	v_mfma_f32_16x16x32_bf16 v[8:11], v[196:199], v[220:223], v[8:11]
	v_mfma_f32_16x16x32_bf16 v[4:7], v[188:191], v[228:231], v[4:7]
	v_mfma_f32_16x16x32_bf16 v[0:3], v[196:199], v[228:231], v[0:3]
	s_setprio 0
	s_barrier
	ds_read_b128 v[144:147], v161
	ds_read_b128 v[170:173], v162
	ds_read_b128 v[176:179], v163
	ds_read_b128 v[180:183], v164
	ds_read_b128 v[184:187], v165
	ds_read_b128 v[188:191], v166
	ds_read_b128 v[192:195], v167
	ds_read_b128 v[196:199], v168
	s_mov_b32 m0, s54
	v_lshl_add_u64 v[236:237], s[50:51], 0, v[128:129]
	ds_read_b128 v[200:203], v151 offset:32768
	ds_read_b128 v[204:207], v151 offset:33792
	ds_read_b128 v[208:211], v151 offset:34816
	ds_read_b128 v[212:215], v151 offset:35840
	ds_read_b128 v[216:219], v151 offset:36864
	ds_read_b128 v[220:223], v151 offset:37888
	ds_read_b128 v[224:227], v151 offset:38912
	ds_read_b128 v[228:231], v151 offset:39936
	global_load_lds_dwordx4 v[236:237], off
	v_lshl_add_u64 v[236:237], s[50:51], 0, v[130:131]
	s_mov_b32 m0, s63
	s_nop 0
	global_load_lds_dwordx4 v[236:237], off
	v_lshl_add_u64 v[236:237], s[50:51], 0, v[132:133]
	s_mov_b32 m0, s64
	s_nop 0
	global_load_lds_dwordx4 v[236:237], off
	v_lshl_add_u64 v[236:237], s[50:51], 0, v[134:135]
	s_mov_b32 m0, s65
	s_nop 0
	global_load_lds_dwordx4 v[236:237], off
	s_waitcnt lgkmcnt(8)
	s_barrier
	s_waitcnt lgkmcnt(0)
	s_setprio 1
	s_waitcnt lgkmcnt(0)
	v_mfma_f32_16x16x32_bf16 v[124:127], v[144:147], v[200:203], v[124:127]
	v_mfma_f32_16x16x32_bf16 v[120:123], v[176:179], v[200:203], v[120:123]
	v_mfma_f32_16x16x32_bf16 v[116:119], v[144:147], v[208:211], v[116:119]
	v_mfma_f32_16x16x32_bf16 v[108:111], v[176:179], v[208:211], v[108:111]
	v_mfma_f32_16x16x32_bf16 v[100:103], v[144:147], v[216:219], v[100:103]
	v_mfma_f32_16x16x32_bf16 v[92:95], v[176:179], v[216:219], v[92:95]
	v_mfma_f32_16x16x32_bf16 v[84:87], v[144:147], v[224:227], v[84:87]
	v_mfma_f32_16x16x32_bf16 v[76:79], v[176:179], v[224:227], v[76:79]
	v_mfma_f32_16x16x32_bf16 v[124:127], v[170:173], v[204:207], v[124:127]
	v_mfma_f32_16x16x32_bf16 v[120:123], v[180:183], v[204:207], v[120:123]
	v_mfma_f32_16x16x32_bf16 v[116:119], v[170:173], v[212:215], v[116:119]
	v_mfma_f32_16x16x32_bf16 v[108:111], v[180:183], v[212:215], v[108:111]
	v_mfma_f32_16x16x32_bf16 v[100:103], v[170:173], v[220:223], v[100:103]
	v_mfma_f32_16x16x32_bf16 v[92:95], v[180:183], v[220:223], v[92:95]
	v_mfma_f32_16x16x32_bf16 v[84:87], v[170:173], v[228:231], v[84:87]
	v_mfma_f32_16x16x32_bf16 v[76:79], v[180:183], v[228:231], v[76:79]
	s_setprio 0
	s_setprio 1
	v_mfma_f32_16x16x32_bf16 v[112:115], v[184:187], v[200:203], v[112:115]
	v_mfma_f32_16x16x32_bf16 v[104:107], v[192:195], v[200:203], v[104:107]
	v_mfma_f32_16x16x32_bf16 v[96:99], v[184:187], v[208:211], v[96:99]
	v_mfma_f32_16x16x32_bf16 v[88:91], v[192:195], v[208:211], v[88:91]
	v_mfma_f32_16x16x32_bf16 v[80:83], v[184:187], v[216:219], v[80:83]
	v_mfma_f32_16x16x32_bf16 v[72:75], v[192:195], v[216:219], v[72:75]
	v_mfma_f32_16x16x32_bf16 v[68:71], v[184:187], v[224:227], v[68:71]
	v_mfma_f32_16x16x32_bf16 v[64:67], v[192:195], v[224:227], v[64:67]
	v_mfma_f32_16x16x32_bf16 v[112:115], v[188:191], v[204:207], v[112:115]
	v_mfma_f32_16x16x32_bf16 v[104:107], v[196:199], v[204:207], v[104:107]
	v_mfma_f32_16x16x32_bf16 v[96:99], v[188:191], v[212:215], v[96:99]
	v_mfma_f32_16x16x32_bf16 v[88:91], v[196:199], v[212:215], v[88:91]
	v_mfma_f32_16x16x32_bf16 v[80:83], v[188:191], v[220:223], v[80:83]
	v_mfma_f32_16x16x32_bf16 v[72:75], v[196:199], v[220:223], v[72:75]
	v_mfma_f32_16x16x32_bf16 v[68:71], v[188:191], v[228:231], v[68:71]
	v_mfma_f32_16x16x32_bf16 v[64:67], v[196:199], v[228:231], v[64:67]
	s_setprio 0
	s_barrier
	s_mov_b32 m0, s66
	v_lshl_add_u64 v[232:233], v[232:233], 0, s[18:19]
	s_add_u32 s48, s48, 0x40080
	ds_read_b128 v[200:203], v151 offset:49152
	ds_read_b128 v[204:207], v151 offset:50176
	ds_read_b128 v[208:211], v151 offset:51200
	ds_read_b128 v[212:215], v151 offset:52224
	ds_read_b128 v[216:219], v151 offset:53248
	ds_read_b128 v[220:223], v151 offset:54272
	ds_read_b128 v[224:227], v151 offset:55296
	ds_read_b128 v[228:231], v151 offset:56320
	global_load_lds_dwordx4 v[232:233], off
	v_lshl_add_u64 v[232:233], v[234:235], 0, s[18:19]
	s_mov_b32 m0, s67
	s_addc_u32 s49, s49, 0
	global_load_lds_dwordx4 v[232:233], off
	v_lshl_add_u64 v[232:233], s[48:49], 0, v[136:137]
	s_mov_b32 m0, s68
	s_nop 0
	global_load_lds_dwordx4 v[232:233], off
	v_lshl_add_u64 v[232:233], s[48:49], 0, v[138:139]
	s_mov_b32 m0, s69
	s_nop 0
	global_load_lds_dwordx4 v[232:233], off
	s_waitcnt vmcnt(4)
	s_waitcnt lgkmcnt(0)
	s_barrier
	s_setprio 1
	s_waitcnt lgkmcnt(0)
	v_mfma_f32_16x16x32_bf16 v[60:63], v[144:147], v[200:203], v[60:63]
	v_mfma_f32_16x16x32_bf16 v[56:59], v[176:179], v[200:203], v[56:59]
	v_mfma_f32_16x16x32_bf16 v[52:55], v[144:147], v[208:211], v[52:55]
	v_mfma_f32_16x16x32_bf16 v[44:47], v[176:179], v[208:211], v[44:47]
	v_mfma_f32_16x16x32_bf16 v[36:39], v[144:147], v[216:219], v[36:39]
	v_mfma_f32_16x16x32_bf16 v[28:31], v[176:179], v[216:219], v[28:31]
	v_mfma_f32_16x16x32_bf16 v[20:23], v[144:147], v[224:227], v[20:23]
	v_mfma_f32_16x16x32_bf16 v[12:15], v[176:179], v[224:227], v[12:15]
	v_mfma_f32_16x16x32_bf16 v[60:63], v[170:173], v[204:207], v[60:63]
	v_mfma_f32_16x16x32_bf16 v[56:59], v[180:183], v[204:207], v[56:59]
	v_mfma_f32_16x16x32_bf16 v[52:55], v[170:173], v[212:215], v[52:55]
	v_mfma_f32_16x16x32_bf16 v[44:47], v[180:183], v[212:215], v[44:47]
	v_mfma_f32_16x16x32_bf16 v[36:39], v[170:173], v[220:223], v[36:39]
	v_mfma_f32_16x16x32_bf16 v[28:31], v[180:183], v[220:223], v[28:31]
	v_mfma_f32_16x16x32_bf16 v[20:23], v[170:173], v[228:231], v[20:23]
	v_mfma_f32_16x16x32_bf16 v[12:15], v[180:183], v[228:231], v[12:15]
	s_setprio 0
	s_setprio 1
	v_mfma_f32_16x16x32_bf16 v[48:51], v[184:187], v[200:203], v[48:51]
	v_mfma_f32_16x16x32_bf16 v[40:43], v[192:195], v[200:203], v[40:43]
	v_mfma_f32_16x16x32_bf16 v[32:35], v[184:187], v[208:211], v[32:35]
	v_mfma_f32_16x16x32_bf16 v[24:27], v[192:195], v[208:211], v[24:27]
	v_mfma_f32_16x16x32_bf16 v[16:19], v[184:187], v[216:219], v[16:19]
	v_mfma_f32_16x16x32_bf16 v[8:11], v[192:195], v[216:219], v[8:11]
	v_mfma_f32_16x16x32_bf16 v[4:7], v[184:187], v[224:227], v[4:7]
	v_mfma_f32_16x16x32_bf16 v[0:3], v[192:195], v[224:227], v[0:3]
	v_mfma_f32_16x16x32_bf16 v[48:51], v[188:191], v[204:207], v[48:51]
	v_mfma_f32_16x16x32_bf16 v[40:43], v[196:199], v[204:207], v[40:43]
	v_mfma_f32_16x16x32_bf16 v[32:35], v[188:191], v[212:215], v[32:35]
	v_mfma_f32_16x16x32_bf16 v[24:27], v[196:199], v[212:215], v[24:27]
	v_mfma_f32_16x16x32_bf16 v[16:19], v[188:191], v[220:223], v[16:19]
	v_mfma_f32_16x16x32_bf16 v[8:11], v[196:199], v[220:223], v[8:11]
	v_mfma_f32_16x16x32_bf16 v[4:7], v[188:191], v[228:231], v[4:7]
	v_mfma_f32_16x16x32_bf16 v[0:3], v[196:199], v[228:231], v[0:3]
	s_setprio 0
	s_cmp_gt_u32 s79, 13
	s_cbranch_scc1 .Lrot_x0
	s_mov_b32 s79, s26
	s_cmp_lg_u32 s79, 14
	s_cselect_b64 s[48:49], -1, 0
	s_or_b64 s[50:51], s[8:9], s[48:49]
	s_or_b64 s[50:51], s[50:51], s[44:45]
	s_and_b64 vcc, exec, s[50:51]
	s_barrier
	s_cbranch_vccnz .LBB0_224
	s_branch .Lrot_a0
.Lrot_x0:
	s_mov_b32 s79, s26
	s_barrier
	s_branch .LBB0_241

.Lrot_a0:
	s_and_saveexec_b64 s[50:51], s[4:5]
	s_cbranch_execz .LBB0_223
	s_memrealtime s[52:53]
	s_mov_b32 s26, 1
	s_branch .LBB0_230

.LBB0_1461:
	s_or_b32 s26, s83, 1
	ds_read_b128 v[144:147], v155
	ds_read_b128 v[176:179], v156
	ds_read_b128 v[180:183], v157
	ds_read_b128 v[184:187], v158
	ds_read_b128 v[188:191], v159
	ds_read_b128 v[192:195], v160
	ds_read_b128 v[196:199], v161
	ds_read_b128 v[200:203], v162
	s_lshl_b64 s[52:53], s[26:27], 7
	s_add_u32 s56, s34, s52
	s_addc_u32 s57, s35, s53
	s_add_i32 s26, s83, 2
	s_lshl_b64 s[58:59], s[26:27], 7
	s_add_u32 s68, s34, s58
	s_addc_u32 s69, s35, s59
	s_and_b64 s[52:53], s[50:51], exec
	s_cselect_b32 s53, s69, s11
	s_cselect_b32 s52, s68, s21
	s_add_u32 s58, s40, s58
	s_addc_u32 s59, s41, s59
	s_and_b64 s[50:51], s[50:51], exec
	s_cselect_b32 s51, s59, s31
	s_cselect_b32 s50, s58, s37
	s_mov_b32 m0, s78
	v_lshl_add_u64 v[148:149], s[56:57], 0, v[128:129]
	ds_read_b128 v[204:207], v153
	ds_read_b128 v[208:211], v153 offset:1024
	ds_read_b128 v[212:215], v153 offset:2048
	ds_read_b128 v[216:219], v153 offset:3072
	ds_read_b128 v[220:223], v153 offset:4096
	ds_read_b128 v[224:227], v153 offset:5120
	ds_read_b128 v[228:231], v153 offset:6144
	ds_read_b128 v[232:235], v153 offset:7168
	global_load_lds_dwordx4 v[148:149], off
	v_lshl_add_u64 v[148:149], s[56:57], 0, v[130:131]
	s_mov_b32 m0, s79
	s_nop 0
	global_load_lds_dwordx4 v[148:149], off
	v_lshl_add_u64 v[148:149], s[56:57], 0, v[132:133]
	s_mov_b32 m0, s80
	s_nop 0
	global_load_lds_dwordx4 v[148:149], off
	v_lshl_add_u64 v[148:149], s[56:57], 0, v[134:135]
	s_mov_b32 m0, s81
	s_nop 0
	global_load_lds_dwordx4 v[148:149], off
	s_waitcnt lgkmcnt(8)
	s_barrier
	s_waitcnt lgkmcnt(0)
	s_setprio 1
	s_waitcnt lgkmcnt(0)
	v_mfma_f32_16x16x32_bf16 v[124:127], v[144:147], v[204:207], v[124:127]
	v_mfma_f32_16x16x32_bf16 v[120:123], v[180:183], v[204:207], v[120:123]
	v_mfma_f32_16x16x32_bf16 v[116:119], v[144:147], v[212:215], v[116:119]
	v_mfma_f32_16x16x32_bf16 v[108:111], v[180:183], v[212:215], v[108:111]
	v_mfma_f32_16x16x32_bf16 v[100:103], v[144:147], v[220:223], v[100:103]
	v_mfma_f32_16x16x32_bf16 v[92:95], v[180:183], v[220:223], v[92:95]
	v_mfma_f32_16x16x32_bf16 v[84:87], v[144:147], v[228:231], v[84:87]
	v_mfma_f32_16x16x32_bf16 v[76:79], v[180:183], v[228:231], v[76:79]
	v_mfma_f32_16x16x32_bf16 v[124:127], v[176:179], v[208:211], v[124:127]
	v_mfma_f32_16x16x32_bf16 v[120:123], v[184:187], v[208:211], v[120:123]
	v_mfma_f32_16x16x32_bf16 v[116:119], v[176:179], v[216:219], v[116:119]
	v_mfma_f32_16x16x32_bf16 v[108:111], v[184:187], v[216:219], v[108:111]
	v_mfma_f32_16x16x32_bf16 v[100:103], v[176:179], v[224:227], v[100:103]
	v_mfma_f32_16x16x32_bf16 v[92:95], v[184:187], v[224:227], v[92:95]
	v_mfma_f32_16x16x32_bf16 v[84:87], v[176:179], v[232:235], v[84:87]
	v_mfma_f32_16x16x32_bf16 v[76:79], v[184:187], v[232:235], v[76:79]
	s_setprio 0
	s_setprio 1
	v_mfma_f32_16x16x32_bf16 v[112:115], v[188:191], v[204:207], v[112:115]
	v_mfma_f32_16x16x32_bf16 v[104:107], v[196:199], v[204:207], v[104:107]
	v_mfma_f32_16x16x32_bf16 v[96:99], v[188:191], v[212:215], v[96:99]
	v_mfma_f32_16x16x32_bf16 v[88:91], v[196:199], v[212:215], v[88:91]
	v_mfma_f32_16x16x32_bf16 v[80:83], v[188:191], v[220:223], v[80:83]
	v_mfma_f32_16x16x32_bf16 v[72:75], v[196:199], v[220:223], v[72:75]
	v_mfma_f32_16x16x32_bf16 v[68:71], v[188:191], v[228:231], v[68:71]
	v_mfma_f32_16x16x32_bf16 v[64:67], v[196:199], v[228:231], v[64:67]
	v_mfma_f32_16x16x32_bf16 v[112:115], v[192:195], v[208:211], v[112:115]
	v_mfma_f32_16x16x32_bf16 v[104:107], v[200:203], v[208:211], v[104:107]
	v_mfma_f32_16x16x32_bf16 v[96:99], v[192:195], v[216:219], v[96:99]
	v_mfma_f32_16x16x32_bf16 v[88:91], v[200:203], v[216:219], v[88:91]
	v_mfma_f32_16x16x32_bf16 v[80:83], v[192:195], v[224:227], v[80:83]
	v_mfma_f32_16x16x32_bf16 v[72:75], v[200:203], v[224:227], v[72:75]
	v_mfma_f32_16x16x32_bf16 v[68:71], v[192:195], v[232:235], v[68:71]
	v_mfma_f32_16x16x32_bf16 v[64:67], v[200:203], v[232:235], v[64:67]
	s_setprio 0
	s_barrier
	s_mov_b32 m0, s61
	v_lshl_add_u64 v[148:149], s[50:51], 0, v[136:137]
	s_add_u32 s56, s50, 0x40000
	ds_read_b128 v[204:207], v153 offset:16384
	ds_read_b128 v[208:211], v153 offset:17408
	ds_read_b128 v[212:215], v153 offset:18432
	ds_read_b128 v[216:219], v153 offset:19456
	ds_read_b128 v[220:223], v153 offset:20480
	ds_read_b128 v[224:227], v153 offset:21504
	ds_read_b128 v[228:231], v153 offset:22528
	ds_read_b128 v[232:235], v153 offset:23552
	global_load_lds_dwordx4 v[148:149], off
	v_lshl_add_u64 v[172:173], s[50:51], 0, v[138:139]
	s_mov_b32 m0, s62
	s_addc_u32 s57, s51, 0
	global_load_lds_dwordx4 v[172:173], off
	v_lshl_add_u64 v[236:237], s[56:57], 0, v[136:137]
	s_mov_b32 m0, s63
	s_nop 0
	global_load_lds_dwordx4 v[236:237], off
	v_lshl_add_u64 v[236:237], s[56:57], 0, v[138:139]
	s_mov_b32 m0, s64
	s_nop 0
	global_load_lds_dwordx4 v[236:237], off
	s_waitcnt vmcnt(4)
	s_waitcnt lgkmcnt(0)
	s_barrier
	s_setprio 1
	s_waitcnt lgkmcnt(0)
	v_mfma_f32_16x16x32_bf16 v[60:63], v[144:147], v[204:207], v[60:63]
	v_mfma_f32_16x16x32_bf16 v[56:59], v[180:183], v[204:207], v[56:59]
	v_mfma_f32_16x16x32_bf16 v[52:55], v[144:147], v[212:215], v[52:55]
	v_mfma_f32_16x16x32_bf16 v[44:47], v[180:183], v[212:215], v[44:47]
	v_mfma_f32_16x16x32_bf16 v[36:39], v[144:147], v[220:223], v[36:39]
	v_mfma_f32_16x16x32_bf16 v[28:31], v[180:183], v[220:223], v[28:31]
	v_mfma_f32_16x16x32_bf16 v[20:23], v[144:147], v[228:231], v[20:23]
	v_mfma_f32_16x16x32_bf16 v[12:15], v[180:183], v[228:231], v[12:15]
	v_mfma_f32_16x16x32_bf16 v[60:63], v[176:179], v[208:211], v[60:63]
	v_mfma_f32_16x16x32_bf16 v[56:59], v[184:187], v[208:211], v[56:59]
	v_mfma_f32_16x16x32_bf16 v[52:55], v[176:179], v[216:219], v[52:55]
	v_mfma_f32_16x16x32_bf16 v[44:47], v[184:187], v[216:219], v[44:47]
	v_mfma_f32_16x16x32_bf16 v[36:39], v[176:179], v[224:227], v[36:39]
	v_mfma_f32_16x16x32_bf16 v[28:31], v[184:187], v[224:227], v[28:31]
	v_mfma_f32_16x16x32_bf16 v[20:23], v[176:179], v[232:235], v[20:23]
	v_mfma_f32_16x16x32_bf16 v[12:15], v[184:187], v[232:235], v[12:15]
	s_setprio 0
	s_setprio 1
	v_mfma_f32_16x16x32_bf16 v[48:51], v[188:191], v[204:207], v[48:51]
	v_mfma_f32_16x16x32_bf16 v[40:43], v[196:199], v[204:207], v[40:43]
	v_mfma_f32_16x16x32_bf16 v[32:35], v[188:191], v[212:215], v[32:35]
	v_mfma_f32_16x16x32_bf16 v[24:27], v[196:199], v[212:215], v[24:27]
	v_mfma_f32_16x16x32_bf16 v[16:19], v[188:191], v[220:223], v[16:19]
	v_mfma_f32_16x16x32_bf16 v[8:11], v[196:199], v[220:223], v[8:11]
	v_mfma_f32_16x16x32_bf16 v[4:7], v[188:191], v[228:231], v[4:7]
	v_mfma_f32_16x16x32_bf16 v[0:3], v[196:199], v[228:231], v[0:3]
	v_mfma_f32_16x16x32_bf16 v[48:51], v[192:195], v[208:211], v[48:51]
	v_mfma_f32_16x16x32_bf16 v[40:43], v[200:203], v[208:211], v[40:43]
	v_mfma_f32_16x16x32_bf16 v[32:35], v[192:195], v[216:219], v[32:35]
	v_mfma_f32_16x16x32_bf16 v[24:27], v[200:203], v[216:219], v[24:27]
	v_mfma_f32_16x16x32_bf16 v[16:19], v[192:195], v[224:227], v[16:19]
	v_mfma_f32_16x16x32_bf16 v[8:11], v[200:203], v[224:227], v[8:11]
	v_mfma_f32_16x16x32_bf16 v[4:7], v[192:195], v[232:235], v[4:7]
	v_mfma_f32_16x16x32_bf16 v[0:3], v[200:203], v[232:235], v[0:3]
	s_setprio 0
	s_barrier
	ds_read_b128 v[144:147], v163
	ds_read_b128 v[176:179], v164
	ds_read_b128 v[180:183], v165
	ds_read_b128 v[184:187], v166
	ds_read_b128 v[188:191], v167
	ds_read_b128 v[192:195], v168
	ds_read_b128 v[196:199], v169
	ds_read_b128 v[200:203], v170
	s_mov_b32 m0, s60
	v_lshl_add_u64 v[236:237], s[52:53], 0, v[128:129]
	ds_read_b128 v[204:207], v153 offset:32768
	ds_read_b128 v[208:211], v153 offset:33792
	ds_read_b128 v[212:215], v153 offset:34816
	ds_read_b128 v[216:219], v153 offset:35840
	ds_read_b128 v[220:223], v153 offset:36864
	ds_read_b128 v[224:227], v153 offset:37888
	ds_read_b128 v[228:231], v153 offset:38912
	ds_read_b128 v[232:235], v153 offset:39936
	global_load_lds_dwordx4 v[236:237], off
	v_lshl_add_u64 v[236:237], s[52:53], 0, v[130:131]
	s_mov_b32 m0, s65
	s_nop 0
	global_load_lds_dwordx4 v[236:237], off
	v_lshl_add_u64 v[236:237], s[52:53], 0, v[132:133]
	s_mov_b32 m0, s66
	s_nop 0
	global_load_lds_dwordx4 v[236:237], off
	v_lshl_add_u64 v[236:237], s[52:53], 0, v[134:135]
	s_mov_b32 m0, s67
	s_nop 0
	global_load_lds_dwordx4 v[236:237], off
	s_waitcnt lgkmcnt(8)
	s_barrier
	s_waitcnt lgkmcnt(0)
	s_setprio 1
	s_waitcnt lgkmcnt(0)
	v_mfma_f32_16x16x32_bf16 v[124:127], v[144:147], v[204:207], v[124:127]
	v_mfma_f32_16x16x32_bf16 v[120:123], v[180:183], v[204:207], v[120:123]
	v_mfma_f32_16x16x32_bf16 v[116:119], v[144:147], v[212:215], v[116:119]
	v_mfma_f32_16x16x32_bf16 v[108:111], v[180:183], v[212:215], v[108:111]
	v_mfma_f32_16x16x32_bf16 v[100:103], v[144:147], v[220:223], v[100:103]
	v_mfma_f32_16x16x32_bf16 v[92:95], v[180:183], v[220:223], v[92:95]
	v_mfma_f32_16x16x32_bf16 v[84:87], v[144:147], v[228:231], v[84:87]
	v_mfma_f32_16x16x32_bf16 v[76:79], v[180:183], v[228:231], v[76:79]
	v_mfma_f32_16x16x32_bf16 v[124:127], v[176:179], v[208:211], v[124:127]
	v_mfma_f32_16x16x32_bf16 v[120:123], v[184:187], v[208:211], v[120:123]
	v_mfma_f32_16x16x32_bf16 v[116:119], v[176:179], v[216:219], v[116:119]
	v_mfma_f32_16x16x32_bf16 v[108:111], v[184:187], v[216:219], v[108:111]
	v_mfma_f32_16x16x32_bf16 v[100:103], v[176:179], v[224:227], v[100:103]
	v_mfma_f32_16x16x32_bf16 v[92:95], v[184:187], v[224:227], v[92:95]
	v_mfma_f32_16x16x32_bf16 v[84:87], v[176:179], v[232:235], v[84:87]
	v_mfma_f32_16x16x32_bf16 v[76:79], v[184:187], v[232:235], v[76:79]
	s_setprio 0
	s_setprio 1
	v_mfma_f32_16x16x32_bf16 v[112:115], v[188:191], v[204:207], v[112:115]
	v_mfma_f32_16x16x32_bf16 v[104:107], v[196:199], v[204:207], v[104:107]
	v_mfma_f32_16x16x32_bf16 v[96:99], v[188:191], v[212:215], v[96:99]
	v_mfma_f32_16x16x32_bf16 v[88:91], v[196:199], v[212:215], v[88:91]
	v_mfma_f32_16x16x32_bf16 v[80:83], v[188:191], v[220:223], v[80:83]
	v_mfma_f32_16x16x32_bf16 v[72:75], v[196:199], v[220:223], v[72:75]
	v_mfma_f32_16x16x32_bf16 v[68:71], v[188:191], v[228:231], v[68:71]
	v_mfma_f32_16x16x32_bf16 v[64:67], v[196:199], v[228:231], v[64:67]
	v_mfma_f32_16x16x32_bf16 v[112:115], v[192:195], v[208:211], v[112:115]
	v_mfma_f32_16x16x32_bf16 v[104:107], v[200:203], v[208:211], v[104:107]
	v_mfma_f32_16x16x32_bf16 v[96:99], v[192:195], v[216:219], v[96:99]
	v_mfma_f32_16x16x32_bf16 v[88:91], v[200:203], v[216:219], v[88:91]
	v_mfma_f32_16x16x32_bf16 v[80:83], v[192:195], v[224:227], v[80:83]
	v_mfma_f32_16x16x32_bf16 v[72:75], v[200:203], v[224:227], v[72:75]
	v_mfma_f32_16x16x32_bf16 v[68:71], v[192:195], v[232:235], v[68:71]
	v_mfma_f32_16x16x32_bf16 v[64:67], v[200:203], v[232:235], v[64:67]
	s_setprio 0
	s_barrier
	s_mov_b32 m0, s72
	v_lshl_add_u64 v[148:149], v[148:149], 0, s[24:25]
	s_add_u32 s50, s50, 0x40080
	ds_read_b128 v[204:207], v153 offset:49152
	ds_read_b128 v[208:211], v153 offset:50176
	ds_read_b128 v[212:215], v153 offset:51200
	ds_read_b128 v[216:219], v153 offset:52224
	ds_read_b128 v[220:223], v153 offset:53248
	ds_read_b128 v[224:227], v153 offset:54272
	ds_read_b128 v[228:231], v153 offset:55296
	ds_read_b128 v[232:235], v153 offset:56320
	global_load_lds_dwordx4 v[148:149], off
	v_lshl_add_u64 v[148:149], v[172:173], 0, s[24:25]
	s_mov_b32 m0, s73
	s_addc_u32 s51, s51, 0
	global_load_lds_dwordx4 v[148:149], off
	v_lshl_add_u64 v[148:149], s[50:51], 0, v[136:137]
	s_mov_b32 m0, s74
	s_nop 0
	global_load_lds_dwordx4 v[148:149], off
	v_lshl_add_u64 v[148:149], s[50:51], 0, v[138:139]
	s_mov_b32 m0, s75
	s_nop 0
	global_load_lds_dwordx4 v[148:149], off
	s_waitcnt vmcnt(4)
	s_waitcnt lgkmcnt(0)
	s_barrier
	s_setprio 1
	s_waitcnt lgkmcnt(0)
	v_mfma_f32_16x16x32_bf16 v[60:63], v[144:147], v[204:207], v[60:63]
	v_mfma_f32_16x16x32_bf16 v[56:59], v[180:183], v[204:207], v[56:59]
	v_mfma_f32_16x16x32_bf16 v[52:55], v[144:147], v[212:215], v[52:55]
	v_mfma_f32_16x16x32_bf16 v[44:47], v[180:183], v[212:215], v[44:47]
	v_mfma_f32_16x16x32_bf16 v[36:39], v[144:147], v[220:223], v[36:39]
	v_mfma_f32_16x16x32_bf16 v[28:31], v[180:183], v[220:223], v[28:31]
	v_mfma_f32_16x16x32_bf16 v[20:23], v[144:147], v[228:231], v[20:23]
	v_mfma_f32_16x16x32_bf16 v[12:15], v[180:183], v[228:231], v[12:15]
	v_mfma_f32_16x16x32_bf16 v[60:63], v[176:179], v[208:211], v[60:63]
	v_mfma_f32_16x16x32_bf16 v[56:59], v[184:187], v[208:211], v[56:59]
	v_mfma_f32_16x16x32_bf16 v[52:55], v[176:179], v[216:219], v[52:55]
	v_mfma_f32_16x16x32_bf16 v[44:47], v[184:187], v[216:219], v[44:47]
	v_mfma_f32_16x16x32_bf16 v[36:39], v[176:179], v[224:227], v[36:39]
	v_mfma_f32_16x16x32_bf16 v[28:31], v[184:187], v[224:227], v[28:31]
	v_mfma_f32_16x16x32_bf16 v[20:23], v[176:179], v[232:235], v[20:23]
	v_mfma_f32_16x16x32_bf16 v[12:15], v[184:187], v[232:235], v[12:15]
	s_setprio 0
	s_setprio 1
	v_mfma_f32_16x16x32_bf16 v[48:51], v[188:191], v[204:207], v[48:51]
	v_mfma_f32_16x16x32_bf16 v[40:43], v[196:199], v[204:207], v[40:43]
	v_mfma_f32_16x16x32_bf16 v[32:35], v[188:191], v[212:215], v[32:35]
	v_mfma_f32_16x16x32_bf16 v[24:27], v[196:199], v[212:215], v[24:27]
	v_mfma_f32_16x16x32_bf16 v[16:19], v[188:191], v[220:223], v[16:19]
	v_mfma_f32_16x16x32_bf16 v[8:11], v[196:199], v[220:223], v[8:11]
	v_mfma_f32_16x16x32_bf16 v[4:7], v[188:191], v[228:231], v[4:7]
	v_mfma_f32_16x16x32_bf16 v[0:3], v[196:199], v[228:231], v[0:3]
	v_mfma_f32_16x16x32_bf16 v[48:51], v[192:195], v[208:211], v[48:51]
	v_mfma_f32_16x16x32_bf16 v[40:43], v[200:203], v[208:211], v[40:43]
	v_mfma_f32_16x16x32_bf16 v[32:35], v[192:195], v[216:219], v[32:35]
	v_mfma_f32_16x16x32_bf16 v[24:27], v[200:203], v[216:219], v[24:27]
	v_mfma_f32_16x16x32_bf16 v[16:19], v[192:195], v[224:227], v[16:19]
	v_mfma_f32_16x16x32_bf16 v[8:11], v[200:203], v[224:227], v[8:11]
	v_mfma_f32_16x16x32_bf16 v[4:7], v[192:195], v[232:235], v[4:7]
	v_mfma_f32_16x16x32_bf16 v[0:3], v[200:203], v[232:235], v[0:3]
	s_setprio 0
	s_cmp_gt_u32 s83, 13
	s_cbranch_scc1 .Lrot_x1
	s_mov_b32 s83, s26
	s_cmp_lg_u32 s83, 14
	s_cselect_b64 s[50:51], -1, 0
	s_or_b64 s[52:53], s[8:9], s[50:51]
	s_or_b64 s[52:53], s[52:53], s[46:47]
	s_and_b64 vcc, exec, s[52:53]
	s_barrier
	s_cbranch_vccnz .LBB0_1461
	s_branch .Lrot_a1
.Lrot_x1:
	s_mov_b32 s83, s26
	s_barrier
	s_branch .LBB0_1478

.Lrot_a1:
	s_and_saveexec_b64 s[52:53], s[4:5]
	s_cbranch_execz .LBB0_1460
	s_memrealtime s[56:57]
	s_mov_b32 s26, 1
	s_branch .LBB0_1467

.LBB0_1732:
	s_or_b32 s20, s84, 1
	ds_read_b128 v[144:147], v154
	ds_read_b128 v[170:173], v155
	ds_read_b128 v[176:179], v156
	ds_read_b128 v[180:183], v157
	ds_read_b128 v[184:187], v158
	ds_read_b128 v[188:191], v159
	ds_read_b128 v[192:195], v160
	ds_read_b128 v[196:199], v161
	s_lshl_b64 s[56:57], s[20:21], 7
	s_add_u32 s58, s46, s56
	s_addc_u32 s59, s47, s57
	s_add_i32 s20, s84, 2
	s_lshl_b64 s[68:69], s[20:21], 7
	s_add_u32 s70, s46, s68
	s_addc_u32 s71, s47, s69
	s_and_b64 s[56:57], s[52:53], exec
	s_cselect_b32 s57, s71, s35
	s_cselect_b32 s56, s70, s43
	s_add_u32 s68, s48, s68
	s_addc_u32 s69, s49, s69
	s_and_b64 s[52:53], s[52:53], exec
	s_cselect_b32 s53, s69, s31
	s_cselect_b32 s52, s68, s83
	s_mov_b32 m0, s77
	v_lshl_add_u64 v[148:149], s[58:59], 0, v[128:129]
	ds_read_b128 v[200:203], v152
	ds_read_b128 v[204:207], v152 offset:1024
	ds_read_b128 v[208:211], v152 offset:2048
	ds_read_b128 v[212:215], v152 offset:3072
	ds_read_b128 v[216:219], v152 offset:4096
	ds_read_b128 v[220:223], v152 offset:5120
	ds_read_b128 v[224:227], v152 offset:6144
	ds_read_b128 v[228:231], v152 offset:7168
	global_load_lds_dwordx4 v[148:149], off
	v_lshl_add_u64 v[148:149], s[58:59], 0, v[130:131]
	s_mov_b32 m0, s78
	s_nop 0
	global_load_lds_dwordx4 v[148:149], off
	v_lshl_add_u64 v[148:149], s[58:59], 0, v[132:133]
	s_mov_b32 m0, s79
	s_nop 0
	global_load_lds_dwordx4 v[148:149], off
	v_lshl_add_u64 v[148:149], s[58:59], 0, v[134:135]
	s_mov_b32 m0, s80
	s_nop 0
	global_load_lds_dwordx4 v[148:149], off
	s_waitcnt lgkmcnt(8)
	s_barrier
	s_waitcnt lgkmcnt(0)
	s_setprio 1
	s_waitcnt lgkmcnt(0)
	v_mfma_f32_16x16x32_bf16 v[120:123], v[144:147], v[200:203], v[120:123]
	v_mfma_f32_16x16x32_bf16 v[124:127], v[176:179], v[200:203], v[124:127]
	v_mfma_f32_16x16x32_bf16 v[104:107], v[144:147], v[208:211], v[104:107]
	v_mfma_f32_16x16x32_bf16 v[108:111], v[176:179], v[208:211], v[108:111]
	v_mfma_f32_16x16x32_bf16 v[88:91], v[144:147], v[216:219], v[88:91]
	v_mfma_f32_16x16x32_bf16 v[92:95], v[176:179], v[216:219], v[92:95]
	v_mfma_f32_16x16x32_bf16 v[72:75], v[144:147], v[224:227], v[72:75]
	v_mfma_f32_16x16x32_bf16 v[76:79], v[176:179], v[224:227], v[76:79]
	v_mfma_f32_16x16x32_bf16 v[120:123], v[170:173], v[204:207], v[120:123]
	v_mfma_f32_16x16x32_bf16 v[124:127], v[180:183], v[204:207], v[124:127]
	v_mfma_f32_16x16x32_bf16 v[104:107], v[170:173], v[212:215], v[104:107]
	v_mfma_f32_16x16x32_bf16 v[108:111], v[180:183], v[212:215], v[108:111]
	v_mfma_f32_16x16x32_bf16 v[88:91], v[170:173], v[220:223], v[88:91]
	v_mfma_f32_16x16x32_bf16 v[92:95], v[180:183], v[220:223], v[92:95]
	v_mfma_f32_16x16x32_bf16 v[72:75], v[170:173], v[228:231], v[72:75]
	v_mfma_f32_16x16x32_bf16 v[76:79], v[180:183], v[228:231], v[76:79]
	s_setprio 0
	s_setprio 1
	v_mfma_f32_16x16x32_bf16 v[112:115], v[184:187], v[200:203], v[112:115]
	v_mfma_f32_16x16x32_bf16 v[116:119], v[192:195], v[200:203], v[116:119]
	v_mfma_f32_16x16x32_bf16 v[96:99], v[184:187], v[208:211], v[96:99]
	v_mfma_f32_16x16x32_bf16 v[100:103], v[192:195], v[208:211], v[100:103]
	v_mfma_f32_16x16x32_bf16 v[80:83], v[184:187], v[216:219], v[80:83]
	v_mfma_f32_16x16x32_bf16 v[84:87], v[192:195], v[216:219], v[84:87]
	v_mfma_f32_16x16x32_bf16 v[64:67], v[184:187], v[224:227], v[64:67]
	v_mfma_f32_16x16x32_bf16 v[68:71], v[192:195], v[224:227], v[68:71]
	v_mfma_f32_16x16x32_bf16 v[112:115], v[188:191], v[204:207], v[112:115]
	v_mfma_f32_16x16x32_bf16 v[116:119], v[196:199], v[204:207], v[116:119]
	v_mfma_f32_16x16x32_bf16 v[96:99], v[188:191], v[212:215], v[96:99]
	v_mfma_f32_16x16x32_bf16 v[100:103], v[196:199], v[212:215], v[100:103]
	v_mfma_f32_16x16x32_bf16 v[80:83], v[188:191], v[220:223], v[80:83]
	v_mfma_f32_16x16x32_bf16 v[84:87], v[196:199], v[220:223], v[84:87]
	v_mfma_f32_16x16x32_bf16 v[64:67], v[188:191], v[228:231], v[64:67]
	v_mfma_f32_16x16x32_bf16 v[68:71], v[196:199], v[228:231], v[68:71]
	s_setprio 0
	s_barrier
	s_mov_b32 m0, s60
	v_lshl_add_u64 v[148:149], s[52:53], 0, v[136:137]
	s_add_u32 s58, s52, 0x40000
	ds_read_b128 v[200:203], v152 offset:16384
	ds_read_b128 v[204:207], v152 offset:17408
	ds_read_b128 v[208:211], v152 offset:18432
	ds_read_b128 v[212:215], v152 offset:19456
	ds_read_b128 v[216:219], v152 offset:20480
	ds_read_b128 v[220:223], v152 offset:21504
	ds_read_b128 v[224:227], v152 offset:22528
	ds_read_b128 v[228:231], v152 offset:23552
	global_load_lds_dwordx4 v[148:149], off
	v_lshl_add_u64 v[232:233], s[52:53], 0, v[138:139]
	s_mov_b32 m0, s61
	s_addc_u32 s59, s53, 0
	global_load_lds_dwordx4 v[232:233], off
	v_lshl_add_u64 v[234:235], s[58:59], 0, v[136:137]
	s_mov_b32 m0, s62
	s_nop 0
	global_load_lds_dwordx4 v[234:235], off
	v_lshl_add_u64 v[234:235], s[58:59], 0, v[138:139]
	s_mov_b32 m0, s63
	s_nop 0
	global_load_lds_dwordx4 v[234:235], off
	s_waitcnt vmcnt(4)
	s_waitcnt lgkmcnt(0)
	s_barrier
	s_setprio 1
	s_waitcnt lgkmcnt(0)
	v_mfma_f32_16x16x32_bf16 v[56:59], v[144:147], v[200:203], v[56:59]
	v_mfma_f32_16x16x32_bf16 v[60:63], v[176:179], v[200:203], v[60:63]
	v_mfma_f32_16x16x32_bf16 v[40:43], v[144:147], v[208:211], v[40:43]
	v_mfma_f32_16x16x32_bf16 v[44:47], v[176:179], v[208:211], v[44:47]
	v_mfma_f32_16x16x32_bf16 v[24:27], v[144:147], v[216:219], v[24:27]
	v_mfma_f32_16x16x32_bf16 v[28:31], v[176:179], v[216:219], v[28:31]
	v_mfma_f32_16x16x32_bf16 v[8:11], v[144:147], v[224:227], v[8:11]
	v_mfma_f32_16x16x32_bf16 v[12:15], v[176:179], v[224:227], v[12:15]
	v_mfma_f32_16x16x32_bf16 v[56:59], v[170:173], v[204:207], v[56:59]
	v_mfma_f32_16x16x32_bf16 v[60:63], v[180:183], v[204:207], v[60:63]
	v_mfma_f32_16x16x32_bf16 v[40:43], v[170:173], v[212:215], v[40:43]
	v_mfma_f32_16x16x32_bf16 v[44:47], v[180:183], v[212:215], v[44:47]
	v_mfma_f32_16x16x32_bf16 v[24:27], v[170:173], v[220:223], v[24:27]
	v_mfma_f32_16x16x32_bf16 v[28:31], v[180:183], v[220:223], v[28:31]
	v_mfma_f32_16x16x32_bf16 v[8:11], v[170:173], v[228:231], v[8:11]
	v_mfma_f32_16x16x32_bf16 v[12:15], v[180:183], v[228:231], v[12:15]
	s_setprio 0
	s_setprio 1
	v_mfma_f32_16x16x32_bf16 v[48:51], v[184:187], v[200:203], v[48:51]
	v_mfma_f32_16x16x32_bf16 v[52:55], v[192:195], v[200:203], v[52:55]
	v_mfma_f32_16x16x32_bf16 v[32:35], v[184:187], v[208:211], v[32:35]
	v_mfma_f32_16x16x32_bf16 v[36:39], v[192:195], v[208:211], v[36:39]
	v_mfma_f32_16x16x32_bf16 v[16:19], v[184:187], v[216:219], v[16:19]
	v_mfma_f32_16x16x32_bf16 v[20:23], v[192:195], v[216:219], v[20:23]
	v_mfma_f32_16x16x32_bf16 v[0:3], v[184:187], v[224:227], v[0:3]
	v_mfma_f32_16x16x32_bf16 v[4:7], v[192:195], v[224:227], v[4:7]
	v_mfma_f32_16x16x32_bf16 v[48:51], v[188:191], v[204:207], v[48:51]
	v_mfma_f32_16x16x32_bf16 v[52:55], v[196:199], v[204:207], v[52:55]
	v_mfma_f32_16x16x32_bf16 v[32:35], v[188:191], v[212:215], v[32:35]
	v_mfma_f32_16x16x32_bf16 v[36:39], v[196:199], v[212:215], v[36:39]
	v_mfma_f32_16x16x32_bf16 v[16:19], v[188:191], v[220:223], v[16:19]
	v_mfma_f32_16x16x32_bf16 v[20:23], v[196:199], v[220:223], v[20:23]
	v_mfma_f32_16x16x32_bf16 v[0:3], v[188:191], v[228:231], v[0:3]
	v_mfma_f32_16x16x32_bf16 v[4:7], v[196:199], v[228:231], v[4:7]
	s_setprio 0
	s_barrier
	ds_read_b128 v[144:147], v162
	ds_read_b128 v[170:173], v163
	ds_read_b128 v[176:179], v164
	ds_read_b128 v[180:183], v165
	ds_read_b128 v[184:187], v166
	ds_read_b128 v[188:191], v167
	ds_read_b128 v[192:195], v168
	ds_read_b128 v[196:199], v169
	s_mov_b32 m0, s45
	v_lshl_add_u64 v[234:235], s[56:57], 0, v[128:129]
	ds_read_b128 v[200:203], v152 offset:32768
	ds_read_b128 v[204:207], v152 offset:33792
	ds_read_b128 v[208:211], v152 offset:34816
	ds_read_b128 v[212:215], v152 offset:35840
	ds_read_b128 v[216:219], v152 offset:36864
	ds_read_b128 v[220:223], v152 offset:37888
	ds_read_b128 v[224:227], v152 offset:38912
	ds_read_b128 v[228:231], v152 offset:39936
	global_load_lds_dwordx4 v[234:235], off
	v_lshl_add_u64 v[234:235], s[56:57], 0, v[130:131]
	s_mov_b32 m0, s64
	s_nop 0
	global_load_lds_dwordx4 v[234:235], off
	v_lshl_add_u64 v[234:235], s[56:57], 0, v[132:133]
	s_mov_b32 m0, s65
	s_nop 0
	global_load_lds_dwordx4 v[234:235], off
	v_lshl_add_u64 v[234:235], s[56:57], 0, v[134:135]
	s_mov_b32 m0, s66
	s_nop 0
	global_load_lds_dwordx4 v[234:235], off
	s_waitcnt lgkmcnt(8)
	s_barrier
	s_waitcnt lgkmcnt(0)
	s_setprio 1
	s_waitcnt lgkmcnt(0)
	v_mfma_f32_16x16x32_bf16 v[120:123], v[144:147], v[200:203], v[120:123]
	v_mfma_f32_16x16x32_bf16 v[124:127], v[176:179], v[200:203], v[124:127]
	v_mfma_f32_16x16x32_bf16 v[104:107], v[144:147], v[208:211], v[104:107]
	v_mfma_f32_16x16x32_bf16 v[108:111], v[176:179], v[208:211], v[108:111]
	v_mfma_f32_16x16x32_bf16 v[88:91], v[144:147], v[216:219], v[88:91]
	v_mfma_f32_16x16x32_bf16 v[92:95], v[176:179], v[216:219], v[92:95]
	v_mfma_f32_16x16x32_bf16 v[72:75], v[144:147], v[224:227], v[72:75]
	v_mfma_f32_16x16x32_bf16 v[76:79], v[176:179], v[224:227], v[76:79]
	v_mfma_f32_16x16x32_bf16 v[120:123], v[170:173], v[204:207], v[120:123]
	v_mfma_f32_16x16x32_bf16 v[124:127], v[180:183], v[204:207], v[124:127]
	v_mfma_f32_16x16x32_bf16 v[104:107], v[170:173], v[212:215], v[104:107]
	v_mfma_f32_16x16x32_bf16 v[108:111], v[180:183], v[212:215], v[108:111]
	v_mfma_f32_16x16x32_bf16 v[88:91], v[170:173], v[220:223], v[88:91]
	v_mfma_f32_16x16x32_bf16 v[92:95], v[180:183], v[220:223], v[92:95]
	v_mfma_f32_16x16x32_bf16 v[72:75], v[170:173], v[228:231], v[72:75]
	v_mfma_f32_16x16x32_bf16 v[76:79], v[180:183], v[228:231], v[76:79]
	s_setprio 0
	s_setprio 1
	v_mfma_f32_16x16x32_bf16 v[112:115], v[184:187], v[200:203], v[112:115]
	v_mfma_f32_16x16x32_bf16 v[116:119], v[192:195], v[200:203], v[116:119]
	v_mfma_f32_16x16x32_bf16 v[96:99], v[184:187], v[208:211], v[96:99]
	v_mfma_f32_16x16x32_bf16 v[100:103], v[192:195], v[208:211], v[100:103]
	v_mfma_f32_16x16x32_bf16 v[80:83], v[184:187], v[216:219], v[80:83]
	v_mfma_f32_16x16x32_bf16 v[84:87], v[192:195], v[216:219], v[84:87]
	v_mfma_f32_16x16x32_bf16 v[64:67], v[184:187], v[224:227], v[64:67]
	v_mfma_f32_16x16x32_bf16 v[68:71], v[192:195], v[224:227], v[68:71]
	v_mfma_f32_16x16x32_bf16 v[112:115], v[188:191], v[204:207], v[112:115]
	v_mfma_f32_16x16x32_bf16 v[116:119], v[196:199], v[204:207], v[116:119]
	v_mfma_f32_16x16x32_bf16 v[96:99], v[188:191], v[212:215], v[96:99]
	v_mfma_f32_16x16x32_bf16 v[100:103], v[196:199], v[212:215], v[100:103]
	v_mfma_f32_16x16x32_bf16 v[80:83], v[188:191], v[220:223], v[80:83]
	v_mfma_f32_16x16x32_bf16 v[84:87], v[196:199], v[220:223], v[84:87]
	v_mfma_f32_16x16x32_bf16 v[64:67], v[188:191], v[228:231], v[64:67]
	v_mfma_f32_16x16x32_bf16 v[68:71], v[196:199], v[228:231], v[68:71]
	s_setprio 0
	s_barrier
	s_mov_b32 m0, s67
	v_lshl_add_u64 v[148:149], v[148:149], 0, s[18:19]
	s_add_u32 s52, s52, 0x40080
	ds_read_b128 v[200:203], v152 offset:49152
	ds_read_b128 v[204:207], v152 offset:50176
	ds_read_b128 v[208:211], v152 offset:51200
	ds_read_b128 v[212:215], v152 offset:52224
	ds_read_b128 v[216:219], v152 offset:53248
	ds_read_b128 v[220:223], v152 offset:54272
	ds_read_b128 v[224:227], v152 offset:55296
	ds_read_b128 v[228:231], v152 offset:56320
	global_load_lds_dwordx4 v[148:149], off
	v_lshl_add_u64 v[148:149], v[232:233], 0, s[18:19]
	s_mov_b32 m0, s72
	s_addc_u32 s53, s53, 0
	global_load_lds_dwordx4 v[148:149], off
	v_lshl_add_u64 v[148:149], s[52:53], 0, v[136:137]
	s_mov_b32 m0, s73
	s_nop 0
	global_load_lds_dwordx4 v[148:149], off
	v_lshl_add_u64 v[148:149], s[52:53], 0, v[138:139]
	s_mov_b32 m0, s74
	s_nop 0
	global_load_lds_dwordx4 v[148:149], off
	s_waitcnt vmcnt(4)
	s_waitcnt lgkmcnt(0)
	s_barrier
	s_setprio 1
	s_waitcnt lgkmcnt(0)
	v_mfma_f32_16x16x32_bf16 v[56:59], v[144:147], v[200:203], v[56:59]
	v_mfma_f32_16x16x32_bf16 v[60:63], v[176:179], v[200:203], v[60:63]
	v_mfma_f32_16x16x32_bf16 v[40:43], v[144:147], v[208:211], v[40:43]
	v_mfma_f32_16x16x32_bf16 v[44:47], v[176:179], v[208:211], v[44:47]
	v_mfma_f32_16x16x32_bf16 v[24:27], v[144:147], v[216:219], v[24:27]
	v_mfma_f32_16x16x32_bf16 v[28:31], v[176:179], v[216:219], v[28:31]
	v_mfma_f32_16x16x32_bf16 v[8:11], v[144:147], v[224:227], v[8:11]
	v_mfma_f32_16x16x32_bf16 v[12:15], v[176:179], v[224:227], v[12:15]
	v_mfma_f32_16x16x32_bf16 v[56:59], v[170:173], v[204:207], v[56:59]
	v_mfma_f32_16x16x32_bf16 v[60:63], v[180:183], v[204:207], v[60:63]
	v_mfma_f32_16x16x32_bf16 v[40:43], v[170:173], v[212:215], v[40:43]
	v_mfma_f32_16x16x32_bf16 v[44:47], v[180:183], v[212:215], v[44:47]
	v_mfma_f32_16x16x32_bf16 v[24:27], v[170:173], v[220:223], v[24:27]
	v_mfma_f32_16x16x32_bf16 v[28:31], v[180:183], v[220:223], v[28:31]
	v_mfma_f32_16x16x32_bf16 v[8:11], v[170:173], v[228:231], v[8:11]
	v_mfma_f32_16x16x32_bf16 v[12:15], v[180:183], v[228:231], v[12:15]
	s_setprio 0
	s_setprio 1
	v_mfma_f32_16x16x32_bf16 v[48:51], v[184:187], v[200:203], v[48:51]
	v_mfma_f32_16x16x32_bf16 v[52:55], v[192:195], v[200:203], v[52:55]
	v_mfma_f32_16x16x32_bf16 v[32:35], v[184:187], v[208:211], v[32:35]
	v_mfma_f32_16x16x32_bf16 v[36:39], v[192:195], v[208:211], v[36:39]
	v_mfma_f32_16x16x32_bf16 v[16:19], v[184:187], v[216:219], v[16:19]
	v_mfma_f32_16x16x32_bf16 v[20:23], v[192:195], v[216:219], v[20:23]
	v_mfma_f32_16x16x32_bf16 v[0:3], v[184:187], v[224:227], v[0:3]
	v_mfma_f32_16x16x32_bf16 v[4:7], v[192:195], v[224:227], v[4:7]
	v_mfma_f32_16x16x32_bf16 v[48:51], v[188:191], v[204:207], v[48:51]
	v_mfma_f32_16x16x32_bf16 v[52:55], v[196:199], v[204:207], v[52:55]
	v_mfma_f32_16x16x32_bf16 v[32:35], v[188:191], v[212:215], v[32:35]
	v_mfma_f32_16x16x32_bf16 v[36:39], v[196:199], v[212:215], v[36:39]
	v_mfma_f32_16x16x32_bf16 v[16:19], v[188:191], v[220:223], v[16:19]
	v_mfma_f32_16x16x32_bf16 v[20:23], v[196:199], v[220:223], v[20:23]
	v_mfma_f32_16x16x32_bf16 v[0:3], v[188:191], v[228:231], v[0:3]
	v_mfma_f32_16x16x32_bf16 v[4:7], v[196:199], v[228:231], v[4:7]
	s_setprio 0
	s_cmp_gt_u32 s84, 13
	s_cbranch_scc1 .Lrot_x2
	s_mov_b32 s84, s20
	s_cmp_lg_u32 s84, 14
	s_cselect_b64 s[52:53], -1, 0
	s_or_b64 s[56:57], s[8:9], s[52:53]
	s_or_b64 s[56:57], s[56:57], s[10:11]
	s_and_b64 vcc, exec, s[56:57]
	s_barrier
	s_cbranch_vccnz .LBB0_1732
	s_branch .Lrot_a2
.Lrot_x2:
	s_mov_b32 s84, s20
	s_barrier
	s_branch .LBB0_1749

.Lrot_a2:
	s_and_saveexec_b64 s[56:57], s[4:5]
	s_cbranch_execz .LBB0_1731
	s_memrealtime s[58:59]
	s_mov_b32 s20, 1
	s_branch .LBB0_1738

.LBB0_1845:
	ds_read_b128 v[180:183], v162
	ds_read_b128 v[184:187], v163
	ds_read_b128 v[188:191], v164
	ds_read_b128 v[192:195], v165
	ds_read_b128 v[196:199], v166
	ds_read_b128 v[200:203], v167
	ds_read_b128 v[204:207], v168
	ds_read_b128 v[208:211], v169
	s_add_u32 s42, s36, s40
	s_addc_u32 s43, s37, s41
	s_add_u32 s42, s42, 0x100
	s_addc_u32 s43, s43, 0
	s_add_u32 s72, s69, s40
	s_addc_u32 s73, s70, s41
	s_cmpk_eq_i32 s40, 0x1f00
	s_cselect_b32 s45, s7, s43
	s_cselect_b32 s44, s21, s42
	s_cselect_b32 s43, s27, s73
	s_cselect_b32 s42, s29, s72
	s_mov_b32 m0, s65
	v_lshl_add_u64 v[244:245], v[156:157], 0, s[40:41]
	ds_read_b128 v[212:215], v160
	ds_read_b128 v[216:219], v160 offset:1024
	ds_read_b128 v[220:223], v160 offset:2048
	ds_read_b128 v[224:227], v160 offset:3072
	ds_read_b128 v[228:231], v160 offset:4096
	ds_read_b128 v[232:235], v160 offset:5120
	ds_read_b128 v[236:239], v160 offset:6144
	ds_read_b128 v[240:243], v160 offset:7168
	global_load_lds_dwordx4 v[244:245], off
	v_lshl_add_u64 v[244:245], v[154:155], 0, s[40:41]
	s_mov_b32 m0, s66
	s_nop 0
	global_load_lds_dwordx4 v[244:245], off
	v_lshl_add_u64 v[244:245], v[152:153], 0, s[40:41]
	s_mov_b32 m0, s67
	s_nop 0
	global_load_lds_dwordx4 v[244:245], off
	v_lshl_add_u64 v[244:245], v[150:151], 0, s[40:41]
	s_mov_b32 m0, s68
	s_nop 0
	global_load_lds_dwordx4 v[244:245], off
	s_waitcnt lgkmcnt(8)
	s_barrier
	s_waitcnt lgkmcnt(0)
	s_setprio 1
	s_waitcnt lgkmcnt(0)
	v_mfma_f32_16x16x32_bf16 v[124:127], v[180:183], v[212:215], v[124:127]
	v_mfma_f32_16x16x32_bf16 v[120:123], v[188:191], v[212:215], v[120:123]
	v_mfma_f32_16x16x32_bf16 v[116:119], v[180:183], v[220:223], v[116:119]
	v_mfma_f32_16x16x32_bf16 v[108:111], v[188:191], v[220:223], v[108:111]
	v_mfma_f32_16x16x32_bf16 v[100:103], v[180:183], v[228:231], v[100:103]
	v_mfma_f32_16x16x32_bf16 v[92:95], v[188:191], v[228:231], v[92:95]
	v_mfma_f32_16x16x32_bf16 v[84:87], v[180:183], v[236:239], v[84:87]
	v_mfma_f32_16x16x32_bf16 v[76:79], v[188:191], v[236:239], v[76:79]
	v_mfma_f32_16x16x32_bf16 v[124:127], v[184:187], v[216:219], v[124:127]
	v_mfma_f32_16x16x32_bf16 v[120:123], v[192:195], v[216:219], v[120:123]
	v_mfma_f32_16x16x32_bf16 v[116:119], v[184:187], v[224:227], v[116:119]
	v_mfma_f32_16x16x32_bf16 v[108:111], v[192:195], v[224:227], v[108:111]
	v_mfma_f32_16x16x32_bf16 v[100:103], v[184:187], v[232:235], v[100:103]
	v_mfma_f32_16x16x32_bf16 v[92:95], v[192:195], v[232:235], v[92:95]
	v_mfma_f32_16x16x32_bf16 v[84:87], v[184:187], v[240:243], v[84:87]
	v_mfma_f32_16x16x32_bf16 v[76:79], v[192:195], v[240:243], v[76:79]
	s_setprio 0
	s_setprio 1
	v_mfma_f32_16x16x32_bf16 v[112:115], v[196:199], v[212:215], v[112:115]
	v_mfma_f32_16x16x32_bf16 v[104:107], v[204:207], v[212:215], v[104:107]
	v_mfma_f32_16x16x32_bf16 v[96:99], v[196:199], v[220:223], v[96:99]
	v_mfma_f32_16x16x32_bf16 v[88:91], v[204:207], v[220:223], v[88:91]
	v_mfma_f32_16x16x32_bf16 v[80:83], v[196:199], v[228:231], v[80:83]
	v_mfma_f32_16x16x32_bf16 v[72:75], v[204:207], v[228:231], v[72:75]
	v_mfma_f32_16x16x32_bf16 v[68:71], v[196:199], v[236:239], v[68:71]
	v_mfma_f32_16x16x32_bf16 v[64:67], v[204:207], v[236:239], v[64:67]
	v_mfma_f32_16x16x32_bf16 v[112:115], v[200:203], v[216:219], v[112:115]
	v_mfma_f32_16x16x32_bf16 v[104:107], v[208:211], v[216:219], v[104:107]
	v_mfma_f32_16x16x32_bf16 v[96:99], v[200:203], v[224:227], v[96:99]
	v_mfma_f32_16x16x32_bf16 v[88:91], v[208:211], v[224:227], v[88:91]
	v_mfma_f32_16x16x32_bf16 v[80:83], v[200:203], v[232:235], v[80:83]
	v_mfma_f32_16x16x32_bf16 v[72:75], v[208:211], v[232:235], v[72:75]
	v_mfma_f32_16x16x32_bf16 v[68:71], v[200:203], v[240:243], v[68:71]
	v_mfma_f32_16x16x32_bf16 v[64:67], v[208:211], v[240:243], v[64:67]
	s_setprio 0
	s_barrier
	s_mov_b32 m0, s50
	v_lshl_add_u64 v[244:245], s[42:43], 0, v[136:137]
	s_add_u32 s72, s42, 0x100000
	ds_read_b128 v[212:215], v160 offset:16384
	ds_read_b128 v[216:219], v160 offset:17408
	ds_read_b128 v[220:223], v160 offset:18432
	ds_read_b128 v[224:227], v160 offset:19456
	ds_read_b128 v[228:231], v160 offset:20480
	ds_read_b128 v[232:235], v160 offset:21504
	ds_read_b128 v[236:239], v160 offset:22528
	ds_read_b128 v[240:243], v160 offset:23552
	global_load_lds_dwordx4 v[244:245], off
	v_lshl_add_u64 v[246:247], s[42:43], 0, v[138:139]
	s_mov_b32 m0, s51
	s_addc_u32 s73, s43, 0
	global_load_lds_dwordx4 v[246:247], off
	v_lshl_add_u64 v[248:249], s[72:73], 0, v[136:137]
	s_mov_b32 m0, s52
	s_nop 0
	global_load_lds_dwordx4 v[248:249], off
	v_lshl_add_u64 v[248:249], s[72:73], 0, v[138:139]
	s_mov_b32 m0, s53
	s_nop 0
	global_load_lds_dwordx4 v[248:249], off
	s_waitcnt vmcnt(4)
	s_waitcnt lgkmcnt(0)
	s_barrier
	s_setprio 1
	s_waitcnt lgkmcnt(0)
	v_mfma_f32_16x16x32_bf16 v[60:63], v[180:183], v[212:215], v[60:63]
	v_mfma_f32_16x16x32_bf16 v[56:59], v[188:191], v[212:215], v[56:59]
	v_mfma_f32_16x16x32_bf16 v[52:55], v[180:183], v[220:223], v[52:55]
	v_mfma_f32_16x16x32_bf16 v[44:47], v[188:191], v[220:223], v[44:47]
	v_mfma_f32_16x16x32_bf16 v[36:39], v[180:183], v[228:231], v[36:39]
	v_mfma_f32_16x16x32_bf16 v[28:31], v[188:191], v[228:231], v[28:31]
	v_mfma_f32_16x16x32_bf16 v[20:23], v[180:183], v[236:239], v[20:23]
	v_mfma_f32_16x16x32_bf16 v[12:15], v[188:191], v[236:239], v[12:15]
	v_mfma_f32_16x16x32_bf16 v[60:63], v[184:187], v[216:219], v[60:63]
	v_mfma_f32_16x16x32_bf16 v[56:59], v[192:195], v[216:219], v[56:59]
	v_mfma_f32_16x16x32_bf16 v[52:55], v[184:187], v[224:227], v[52:55]
	v_mfma_f32_16x16x32_bf16 v[44:47], v[192:195], v[224:227], v[44:47]
	v_mfma_f32_16x16x32_bf16 v[36:39], v[184:187], v[232:235], v[36:39]
	v_mfma_f32_16x16x32_bf16 v[28:31], v[192:195], v[232:235], v[28:31]
	v_mfma_f32_16x16x32_bf16 v[20:23], v[184:187], v[240:243], v[20:23]
	v_mfma_f32_16x16x32_bf16 v[12:15], v[192:195], v[240:243], v[12:15]
	s_setprio 0
	s_setprio 1
	v_mfma_f32_16x16x32_bf16 v[48:51], v[196:199], v[212:215], v[48:51]
	v_mfma_f32_16x16x32_bf16 v[40:43], v[204:207], v[212:215], v[40:43]
	v_mfma_f32_16x16x32_bf16 v[32:35], v[196:199], v[220:223], v[32:35]
	v_mfma_f32_16x16x32_bf16 v[24:27], v[204:207], v[220:223], v[24:27]
	v_mfma_f32_16x16x32_bf16 v[16:19], v[196:199], v[228:231], v[16:19]
	v_mfma_f32_16x16x32_bf16 v[8:11], v[204:207], v[228:231], v[8:11]
	v_mfma_f32_16x16x32_bf16 v[4:7], v[196:199], v[236:239], v[4:7]
	v_mfma_f32_16x16x32_bf16 v[0:3], v[204:207], v[236:239], v[0:3]
	v_mfma_f32_16x16x32_bf16 v[48:51], v[200:203], v[216:219], v[48:51]
	v_mfma_f32_16x16x32_bf16 v[40:43], v[208:211], v[216:219], v[40:43]
	v_mfma_f32_16x16x32_bf16 v[32:35], v[200:203], v[224:227], v[32:35]
	v_mfma_f32_16x16x32_bf16 v[24:27], v[208:211], v[224:227], v[24:27]
	v_mfma_f32_16x16x32_bf16 v[16:19], v[200:203], v[232:235], v[16:19]
	v_mfma_f32_16x16x32_bf16 v[8:11], v[208:211], v[232:235], v[8:11]
	v_mfma_f32_16x16x32_bf16 v[4:7], v[200:203], v[240:243], v[4:7]
	v_mfma_f32_16x16x32_bf16 v[0:3], v[208:211], v[240:243], v[0:3]
	s_setprio 0
	s_barrier
	ds_read_b128 v[180:183], v170
	ds_read_b128 v[184:187], v171
	ds_read_b128 v[188:191], v172
	ds_read_b128 v[192:195], v173
	ds_read_b128 v[196:199], v176
	ds_read_b128 v[200:203], v177
	ds_read_b128 v[204:207], v178
	ds_read_b128 v[208:211], v179
	s_mov_b32 m0, s49
	v_lshl_add_u64 v[248:249], s[44:45], 0, v[128:129]
	ds_read_b128 v[212:215], v160 offset:32768
	ds_read_b128 v[216:219], v160 offset:33792
	ds_read_b128 v[220:223], v160 offset:34816
	ds_read_b128 v[224:227], v160 offset:35840
	ds_read_b128 v[228:231], v160 offset:36864
	ds_read_b128 v[232:235], v160 offset:37888
	ds_read_b128 v[236:239], v160 offset:38912
	ds_read_b128 v[240:243], v160 offset:39936
	global_load_lds_dwordx4 v[248:249], off
	v_lshl_add_u64 v[248:249], s[44:45], 0, v[130:131]
	s_mov_b32 m0, s54
	s_nop 0
	global_load_lds_dwordx4 v[248:249], off
	v_lshl_add_u64 v[248:249], s[44:45], 0, v[132:133]
	s_mov_b32 m0, s55
	s_nop 0
	global_load_lds_dwordx4 v[248:249], off
	v_lshl_add_u64 v[248:249], s[44:45], 0, v[134:135]
	s_mov_b32 m0, s56
	s_nop 0
	global_load_lds_dwordx4 v[248:249], off
	s_waitcnt lgkmcnt(8)
	s_barrier
	s_waitcnt lgkmcnt(0)
	s_setprio 1
	s_waitcnt lgkmcnt(0)
	v_mfma_f32_16x16x32_bf16 v[124:127], v[180:183], v[212:215], v[124:127]
	v_mfma_f32_16x16x32_bf16 v[120:123], v[188:191], v[212:215], v[120:123]
	v_mfma_f32_16x16x32_bf16 v[116:119], v[180:183], v[220:223], v[116:119]
	v_mfma_f32_16x16x32_bf16 v[108:111], v[188:191], v[220:223], v[108:111]
	v_mfma_f32_16x16x32_bf16 v[100:103], v[180:183], v[228:231], v[100:103]
	v_mfma_f32_16x16x32_bf16 v[92:95], v[188:191], v[228:231], v[92:95]
	v_mfma_f32_16x16x32_bf16 v[84:87], v[180:183], v[236:239], v[84:87]
	v_mfma_f32_16x16x32_bf16 v[76:79], v[188:191], v[236:239], v[76:79]
	v_mfma_f32_16x16x32_bf16 v[124:127], v[184:187], v[216:219], v[124:127]
	v_mfma_f32_16x16x32_bf16 v[120:123], v[192:195], v[216:219], v[120:123]
	v_mfma_f32_16x16x32_bf16 v[116:119], v[184:187], v[224:227], v[116:119]
	v_mfma_f32_16x16x32_bf16 v[108:111], v[192:195], v[224:227], v[108:111]
	v_mfma_f32_16x16x32_bf16 v[100:103], v[184:187], v[232:235], v[100:103]
	v_mfma_f32_16x16x32_bf16 v[92:95], v[192:195], v[232:235], v[92:95]
	v_mfma_f32_16x16x32_bf16 v[84:87], v[184:187], v[240:243], v[84:87]
	v_mfma_f32_16x16x32_bf16 v[76:79], v[192:195], v[240:243], v[76:79]
	s_setprio 0
	s_setprio 1
	v_mfma_f32_16x16x32_bf16 v[112:115], v[196:199], v[212:215], v[112:115]
	v_mfma_f32_16x16x32_bf16 v[104:107], v[204:207], v[212:215], v[104:107]
	v_mfma_f32_16x16x32_bf16 v[96:99], v[196:199], v[220:223], v[96:99]
	v_mfma_f32_16x16x32_bf16 v[88:91], v[204:207], v[220:223], v[88:91]
	v_mfma_f32_16x16x32_bf16 v[80:83], v[196:199], v[228:231], v[80:83]
	v_mfma_f32_16x16x32_bf16 v[72:75], v[204:207], v[228:231], v[72:75]
	v_mfma_f32_16x16x32_bf16 v[68:71], v[196:199], v[236:239], v[68:71]
	v_mfma_f32_16x16x32_bf16 v[64:67], v[204:207], v[236:239], v[64:67]
	v_mfma_f32_16x16x32_bf16 v[112:115], v[200:203], v[216:219], v[112:115]
	v_mfma_f32_16x16x32_bf16 v[104:107], v[208:211], v[216:219], v[104:107]
	v_mfma_f32_16x16x32_bf16 v[96:99], v[200:203], v[224:227], v[96:99]
	v_mfma_f32_16x16x32_bf16 v[88:91], v[208:211], v[224:227], v[88:91]
	v_mfma_f32_16x16x32_bf16 v[80:83], v[200:203], v[232:235], v[80:83]
	v_mfma_f32_16x16x32_bf16 v[72:75], v[208:211], v[232:235], v[72:75]
	v_mfma_f32_16x16x32_bf16 v[68:71], v[200:203], v[240:243], v[68:71]
	v_mfma_f32_16x16x32_bf16 v[64:67], v[208:211], v[240:243], v[64:67]
	s_setprio 0
	s_barrier
	s_mov_b32 m0, s58
	v_lshl_add_u64 v[244:245], v[244:245], 0, s[14:15]
	s_add_u32 s42, s42, 0x100080
	ds_read_b128 v[212:215], v160 offset:49152
	ds_read_b128 v[216:219], v160 offset:50176
	ds_read_b128 v[220:223], v160 offset:51200
	ds_read_b128 v[224:227], v160 offset:52224
	ds_read_b128 v[228:231], v160 offset:53248
	ds_read_b128 v[232:235], v160 offset:54272
	ds_read_b128 v[236:239], v160 offset:55296
	ds_read_b128 v[240:243], v160 offset:56320
	global_load_lds_dwordx4 v[244:245], off
	v_lshl_add_u64 v[244:245], v[246:247], 0, s[14:15]
	s_mov_b32 m0, s59
	s_addc_u32 s43, s43, 0
	global_load_lds_dwordx4 v[244:245], off
	v_lshl_add_u64 v[244:245], s[42:43], 0, v[136:137]
	s_mov_b32 m0, s60
	s_nop 0
	global_load_lds_dwordx4 v[244:245], off
	v_lshl_add_u64 v[244:245], s[42:43], 0, v[138:139]
	s_mov_b32 m0, s61
	s_nop 0
	global_load_lds_dwordx4 v[244:245], off
	s_waitcnt vmcnt(4)
	s_waitcnt lgkmcnt(0)
	s_barrier
	s_setprio 1
	s_waitcnt lgkmcnt(0)
	v_mfma_f32_16x16x32_bf16 v[60:63], v[180:183], v[212:215], v[60:63]
	v_mfma_f32_16x16x32_bf16 v[56:59], v[188:191], v[212:215], v[56:59]
	v_mfma_f32_16x16x32_bf16 v[52:55], v[180:183], v[220:223], v[52:55]
	v_mfma_f32_16x16x32_bf16 v[44:47], v[188:191], v[220:223], v[44:47]
	v_mfma_f32_16x16x32_bf16 v[36:39], v[180:183], v[228:231], v[36:39]
	v_mfma_f32_16x16x32_bf16 v[28:31], v[188:191], v[228:231], v[28:31]
	v_mfma_f32_16x16x32_bf16 v[20:23], v[180:183], v[236:239], v[20:23]
	v_mfma_f32_16x16x32_bf16 v[12:15], v[188:191], v[236:239], v[12:15]
	v_mfma_f32_16x16x32_bf16 v[60:63], v[184:187], v[216:219], v[60:63]
	v_mfma_f32_16x16x32_bf16 v[56:59], v[192:195], v[216:219], v[56:59]
	v_mfma_f32_16x16x32_bf16 v[52:55], v[184:187], v[224:227], v[52:55]
	v_mfma_f32_16x16x32_bf16 v[44:47], v[192:195], v[224:227], v[44:47]
	v_mfma_f32_16x16x32_bf16 v[36:39], v[184:187], v[232:235], v[36:39]
	v_mfma_f32_16x16x32_bf16 v[28:31], v[192:195], v[232:235], v[28:31]
	v_mfma_f32_16x16x32_bf16 v[20:23], v[184:187], v[240:243], v[20:23]
	v_mfma_f32_16x16x32_bf16 v[12:15], v[192:195], v[240:243], v[12:15]
	s_setprio 0
	s_setprio 1
	v_mfma_f32_16x16x32_bf16 v[48:51], v[196:199], v[212:215], v[48:51]
	v_mfma_f32_16x16x32_bf16 v[40:43], v[204:207], v[212:215], v[40:43]
	v_mfma_f32_16x16x32_bf16 v[32:35], v[196:199], v[220:223], v[32:35]
	v_mfma_f32_16x16x32_bf16 v[24:27], v[204:207], v[220:223], v[24:27]
	v_mfma_f32_16x16x32_bf16 v[16:19], v[196:199], v[228:231], v[16:19]
	v_mfma_f32_16x16x32_bf16 v[8:11], v[204:207], v[228:231], v[8:11]
	v_mfma_f32_16x16x32_bf16 v[4:7], v[196:199], v[236:239], v[4:7]
	v_mfma_f32_16x16x32_bf16 v[0:3], v[204:207], v[236:239], v[0:3]
	v_mfma_f32_16x16x32_bf16 v[48:51], v[200:203], v[216:219], v[48:51]
	v_mfma_f32_16x16x32_bf16 v[40:43], v[208:211], v[216:219], v[40:43]
	v_mfma_f32_16x16x32_bf16 v[32:35], v[200:203], v[224:227], v[32:35]
	v_mfma_f32_16x16x32_bf16 v[24:27], v[208:211], v[224:227], v[24:27]
	v_mfma_f32_16x16x32_bf16 v[16:19], v[200:203], v[232:235], v[16:19]
	v_mfma_f32_16x16x32_bf16 v[8:11], v[208:211], v[232:235], v[8:11]
	v_mfma_f32_16x16x32_bf16 v[4:7], v[200:203], v[240:243], v[4:7]
	v_mfma_f32_16x16x32_bf16 v[0:3], v[208:211], v[240:243], v[0:3]
	s_setprio 0
	s_add_i32 s71, s71, 2
	s_add_u32 s40, s40, 0x100
	s_addc_u32 s41, s41, 0
	s_cmp_gt_u32 s71, 61
	s_barrier
	s_cbranch_scc0 .LBB0_1845
	v_lshl_add_u32 v152, s20, 8, v159
	v_ashrrev_i32_e32 v153, 31, v152
	v_lshl_or_b32 v150, s6, 8, v161
	v_lshlrev_b64 v[154:155], 11, v[152:153]
	v_ashrrev_i32_e32 v151, 31, v150
	v_lshl_add_u64 v[154:155], s[12:13], 0, v[154:155]
	v_lshl_add_u64 v[154:155], v[150:151], 1, v[154:155]
	v_cmp_gt_i32_e32 vcc, s57, v150
	s_and_saveexec_b64 s[6:7], vcc
	s_cbranch_execz .LBB0_1848
	v_cvt_pk_bf16_f32 v124, v124, v125
	v_cvt_pk_bf16_f32 v125, v126, v127
	v_cvt_pk_bf16_f32 v126, v120, v121
	v_cvt_pk_bf16_f32 v127, v122, v123
	flat_store_dwordx4 v[154:155], v[124:127]

.LBB0_2124:
	s_or_b32 s22, s75, 1
	ds_read_b128 v[112:115], v120
	ds_read_b128 v[136:139], v121
	ds_read_b128 v[140:143], v122
	ds_read_b128 v[144:147], v123
	ds_read_b128 v[148:151], v124
	ds_read_b128 v[152:155], v125
	ds_read_b128 v[156:159], v126
	ds_read_b128 v[160:163], v127
	s_lshl_b64 s[44:45], s[22:23], 7
	s_add_u32 s46, s24, s44
	s_addc_u32 s47, s25, s45
	s_add_i32 s22, s75, 2
	s_lshl_b64 s[48:49], s[22:23], 7
	s_add_u32 s50, s24, s48
	s_addc_u32 s51, s25, s49
	s_and_b64 s[44:45], s[42:43], exec
	s_cselect_b32 s45, s51, s31
	s_cselect_b32 s44, s50, s30
	s_add_u32 s48, s26, s48
	s_addc_u32 s49, s27, s49
	s_and_b64 s[42:43], s[42:43], exec
	s_cselect_b32 s43, s49, s15
	s_cselect_b32 s42, s48, s29
	s_mov_b32 m0, s68
	v_lshl_add_u64 v[172:173], s[46:47], 0, v[96:97]
	ds_read_b128 v[164:167], v118
	ds_read_b128 v[168:171], v118 offset:1024
	ds_read_b128 v[176:179], v118 offset:2048
	ds_read_b128 v[180:183], v118 offset:3072
	ds_read_b128 v[184:187], v118 offset:4096
	ds_read_b128 v[188:191], v118 offset:5120
	global_load_lds_dwordx4 v[172:173], off
	v_lshl_add_u64 v[172:173], s[46:47], 0, v[98:99]
	s_mov_b32 m0, s69
	s_nop 0
	global_load_lds_dwordx4 v[172:173], off
	v_lshl_add_u64 v[172:173], s[46:47], 0, v[100:101]
	s_mov_b32 m0, s70
	s_nop 0
	global_load_lds_dwordx4 v[172:173], off
	s_waitcnt lgkmcnt(6)
	s_barrier
	s_waitcnt lgkmcnt(0)
	s_setprio 1
	s_waitcnt lgkmcnt(0)
	v_mfma_f32_16x16x32_bf16 v[92:95], v[112:115], v[164:167], v[92:95]
	v_mfma_f32_16x16x32_bf16 v[88:91], v[140:143], v[164:167], v[88:91]
	v_mfma_f32_16x16x32_bf16 v[80:83], v[112:115], v[176:179], v[80:83]
	v_mfma_f32_16x16x32_bf16 v[72:75], v[140:143], v[176:179], v[72:75]
	v_mfma_f32_16x16x32_bf16 v[64:67], v[112:115], v[184:187], v[64:67]
	v_mfma_f32_16x16x32_bf16 v[56:59], v[140:143], v[184:187], v[56:59]
	v_mfma_f32_16x16x32_bf16 v[92:95], v[136:139], v[168:171], v[92:95]
	v_mfma_f32_16x16x32_bf16 v[88:91], v[144:147], v[168:171], v[88:91]
	v_mfma_f32_16x16x32_bf16 v[80:83], v[136:139], v[180:183], v[80:83]
	v_mfma_f32_16x16x32_bf16 v[72:75], v[144:147], v[180:183], v[72:75]
	v_mfma_f32_16x16x32_bf16 v[64:67], v[136:139], v[188:191], v[64:67]
	v_mfma_f32_16x16x32_bf16 v[56:59], v[144:147], v[188:191], v[56:59]
	s_setprio 0
	s_setprio 1
	v_mfma_f32_16x16x32_bf16 v[84:87], v[148:151], v[164:167], v[84:87]
	v_mfma_f32_16x16x32_bf16 v[76:79], v[156:159], v[164:167], v[76:79]
	v_mfma_f32_16x16x32_bf16 v[68:71], v[148:151], v[176:179], v[68:71]
	v_mfma_f32_16x16x32_bf16 v[60:63], v[156:159], v[176:179], v[60:63]
	v_mfma_f32_16x16x32_bf16 v[52:55], v[148:151], v[184:187], v[52:55]
	v_mfma_f32_16x16x32_bf16 v[48:51], v[156:159], v[184:187], v[48:51]
	v_mfma_f32_16x16x32_bf16 v[84:87], v[152:155], v[168:171], v[84:87]
	v_mfma_f32_16x16x32_bf16 v[76:79], v[160:163], v[168:171], v[76:79]
	v_mfma_f32_16x16x32_bf16 v[68:71], v[152:155], v[180:183], v[68:71]
	v_mfma_f32_16x16x32_bf16 v[60:63], v[160:163], v[180:183], v[60:63]
	v_mfma_f32_16x16x32_bf16 v[52:55], v[152:155], v[188:191], v[52:55]
	v_mfma_f32_16x16x32_bf16 v[48:51], v[160:163], v[188:191], v[48:51]
	s_setprio 0
	s_barrier
	s_mov_b32 m0, s56
	v_lshl_add_u64 v[172:173], s[42:43], 0, v[102:103]
	s_add_u32 s46, s42, 0x40000
	ds_read_b128 v[164:167], v118 offset:12288
	ds_read_b128 v[168:171], v118 offset:13312
	ds_read_b128 v[176:179], v118 offset:14336
	ds_read_b128 v[180:183], v118 offset:15360
	ds_read_b128 v[184:187], v118 offset:16384
	ds_read_b128 v[188:191], v118 offset:17408
	global_load_lds_dwordx4 v[172:173], off
	v_lshl_add_u64 v[192:193], s[42:43], 0, v[104:105]
	s_mov_b32 m0, s57
	s_addc_u32 s47, s43, 0
	global_load_lds_dwordx4 v[192:193], off
	v_lshl_add_u64 v[194:195], s[46:47], 0, v[102:103]
	s_mov_b32 m0, s58
	s_nop 0
	global_load_lds_dwordx4 v[194:195], off
	v_lshl_add_u64 v[194:195], s[46:47], 0, v[104:105]
	s_mov_b32 m0, s59
	s_nop 0
	global_load_lds_dwordx4 v[194:195], off
	s_waitcnt vmcnt(4)
	s_waitcnt lgkmcnt(0)
	s_barrier
	s_setprio 1
	s_waitcnt lgkmcnt(0)
	v_mfma_f32_16x16x32_bf16 v[44:47], v[112:115], v[164:167], v[44:47]
	v_mfma_f32_16x16x32_bf16 v[40:43], v[140:143], v[164:167], v[40:43]
	v_mfma_f32_16x16x32_bf16 v[32:35], v[112:115], v[176:179], v[32:35]
	v_mfma_f32_16x16x32_bf16 v[24:27], v[140:143], v[176:179], v[24:27]
	v_mfma_f32_16x16x32_bf16 v[16:19], v[112:115], v[184:187], v[16:19]
	v_mfma_f32_16x16x32_bf16 v[8:11], v[140:143], v[184:187], v[8:11]
	v_mfma_f32_16x16x32_bf16 v[44:47], v[136:139], v[168:171], v[44:47]
	v_mfma_f32_16x16x32_bf16 v[40:43], v[144:147], v[168:171], v[40:43]
	v_mfma_f32_16x16x32_bf16 v[32:35], v[136:139], v[180:183], v[32:35]
	v_mfma_f32_16x16x32_bf16 v[24:27], v[144:147], v[180:183], v[24:27]
	v_mfma_f32_16x16x32_bf16 v[16:19], v[136:139], v[188:191], v[16:19]
	v_mfma_f32_16x16x32_bf16 v[8:11], v[144:147], v[188:191], v[8:11]
	s_setprio 0
	s_setprio 1
	v_mfma_f32_16x16x32_bf16 v[36:39], v[148:151], v[164:167], v[36:39]
	v_mfma_f32_16x16x32_bf16 v[28:31], v[156:159], v[164:167], v[28:31]
	v_mfma_f32_16x16x32_bf16 v[20:23], v[148:151], v[176:179], v[20:23]
	v_mfma_f32_16x16x32_bf16 v[12:15], v[156:159], v[176:179], v[12:15]
	v_mfma_f32_16x16x32_bf16 v[4:7], v[148:151], v[184:187], v[4:7]
	v_mfma_f32_16x16x32_bf16 v[0:3], v[156:159], v[184:187], v[0:3]
	v_mfma_f32_16x16x32_bf16 v[36:39], v[152:155], v[168:171], v[36:39]
	v_mfma_f32_16x16x32_bf16 v[28:31], v[160:163], v[168:171], v[28:31]
	v_mfma_f32_16x16x32_bf16 v[20:23], v[152:155], v[180:183], v[20:23]
	v_mfma_f32_16x16x32_bf16 v[12:15], v[160:163], v[180:183], v[12:15]
	v_mfma_f32_16x16x32_bf16 v[4:7], v[152:155], v[188:191], v[4:7]
	v_mfma_f32_16x16x32_bf16 v[0:3], v[160:163], v[188:191], v[0:3]
	s_setprio 0
	s_barrier
	ds_read_b128 v[112:115], v128
	ds_read_b128 v[136:139], v129
	ds_read_b128 v[140:143], v130
	ds_read_b128 v[144:147], v131
	ds_read_b128 v[148:151], v132
	ds_read_b128 v[152:155], v133
	ds_read_b128 v[156:159], v134
	ds_read_b128 v[160:163], v135
	s_mov_b32 m0, s55
	v_lshl_add_u64 v[194:195], s[44:45], 0, v[96:97]
	ds_read_b128 v[164:167], v118 offset:32768
	ds_read_b128 v[168:171], v118 offset:33792
	ds_read_b128 v[176:179], v118 offset:34816
	ds_read_b128 v[180:183], v118 offset:35840
	ds_read_b128 v[184:187], v118 offset:36864
	ds_read_b128 v[188:191], v118 offset:37888
	global_load_lds_dwordx4 v[194:195], off
	v_lshl_add_u64 v[194:195], s[44:45], 0, v[98:99]
	s_mov_b32 m0, s60
	s_nop 0
	global_load_lds_dwordx4 v[194:195], off
	v_lshl_add_u64 v[194:195], s[44:45], 0, v[100:101]
	s_mov_b32 m0, s61
	s_nop 0
	global_load_lds_dwordx4 v[194:195], off
	s_waitcnt lgkmcnt(6)
	s_barrier
	s_waitcnt lgkmcnt(0)
	s_setprio 1
	s_waitcnt lgkmcnt(0)
	v_mfma_f32_16x16x32_bf16 v[92:95], v[112:115], v[164:167], v[92:95]
	v_mfma_f32_16x16x32_bf16 v[88:91], v[140:143], v[164:167], v[88:91]
	v_mfma_f32_16x16x32_bf16 v[80:83], v[112:115], v[176:179], v[80:83]
	v_mfma_f32_16x16x32_bf16 v[72:75], v[140:143], v[176:179], v[72:75]
	v_mfma_f32_16x16x32_bf16 v[64:67], v[112:115], v[184:187], v[64:67]
	v_mfma_f32_16x16x32_bf16 v[56:59], v[140:143], v[184:187], v[56:59]
	v_mfma_f32_16x16x32_bf16 v[92:95], v[136:139], v[168:171], v[92:95]
	v_mfma_f32_16x16x32_bf16 v[88:91], v[144:147], v[168:171], v[88:91]
	v_mfma_f32_16x16x32_bf16 v[80:83], v[136:139], v[180:183], v[80:83]
	v_mfma_f32_16x16x32_bf16 v[72:75], v[144:147], v[180:183], v[72:75]
	v_mfma_f32_16x16x32_bf16 v[64:67], v[136:139], v[188:191], v[64:67]
	v_mfma_f32_16x16x32_bf16 v[56:59], v[144:147], v[188:191], v[56:59]
	s_setprio 0
	s_setprio 1
	v_mfma_f32_16x16x32_bf16 v[84:87], v[148:151], v[164:167], v[84:87]
	v_mfma_f32_16x16x32_bf16 v[76:79], v[156:159], v[164:167], v[76:79]
	v_mfma_f32_16x16x32_bf16 v[68:71], v[148:151], v[176:179], v[68:71]
	v_mfma_f32_16x16x32_bf16 v[60:63], v[156:159], v[176:179], v[60:63]
	v_mfma_f32_16x16x32_bf16 v[52:55], v[148:151], v[184:187], v[52:55]
	v_mfma_f32_16x16x32_bf16 v[48:51], v[156:159], v[184:187], v[48:51]
	v_mfma_f32_16x16x32_bf16 v[84:87], v[152:155], v[168:171], v[84:87]
	v_mfma_f32_16x16x32_bf16 v[76:79], v[160:163], v[168:171], v[76:79]
	v_mfma_f32_16x16x32_bf16 v[68:71], v[152:155], v[180:183], v[68:71]
	v_mfma_f32_16x16x32_bf16 v[60:63], v[160:163], v[180:183], v[60:63]
	v_mfma_f32_16x16x32_bf16 v[52:55], v[152:155], v[188:191], v[52:55]
	v_mfma_f32_16x16x32_bf16 v[48:51], v[160:163], v[188:191], v[48:51]
	s_setprio 0
	s_barrier
	s_mov_b32 m0, s62
	v_lshl_add_u64 v[172:173], v[172:173], 0, s[20:21]
	s_add_u32 s42, s42, 0x40080
	ds_read_b128 v[164:167], v118 offset:45056
	ds_read_b128 v[168:171], v118 offset:46080
	ds_read_b128 v[176:179], v118 offset:47104
	ds_read_b128 v[180:183], v118 offset:48128
	ds_read_b128 v[184:187], v118 offset:49152
	ds_read_b128 v[188:191], v118 offset:50176
	global_load_lds_dwordx4 v[172:173], off
	v_lshl_add_u64 v[172:173], v[192:193], 0, s[20:21]
	s_mov_b32 m0, s63
	s_addc_u32 s43, s43, 0
	global_load_lds_dwordx4 v[172:173], off
	v_lshl_add_u64 v[172:173], s[42:43], 0, v[102:103]
	s_mov_b32 m0, s64
	s_nop 0
	global_load_lds_dwordx4 v[172:173], off
	v_lshl_add_u64 v[172:173], s[42:43], 0, v[104:105]
	s_mov_b32 m0, s65
	s_nop 0
	global_load_lds_dwordx4 v[172:173], off
	s_waitcnt vmcnt(4)
	s_waitcnt lgkmcnt(0)
	s_barrier
	s_setprio 1
	s_waitcnt lgkmcnt(0)
	v_mfma_f32_16x16x32_bf16 v[44:47], v[112:115], v[164:167], v[44:47]
	v_mfma_f32_16x16x32_bf16 v[40:43], v[140:143], v[164:167], v[40:43]
	v_mfma_f32_16x16x32_bf16 v[32:35], v[112:115], v[176:179], v[32:35]
	v_mfma_f32_16x16x32_bf16 v[24:27], v[140:143], v[176:179], v[24:27]
	v_mfma_f32_16x16x32_bf16 v[16:19], v[112:115], v[184:187], v[16:19]
	v_mfma_f32_16x16x32_bf16 v[8:11], v[140:143], v[184:187], v[8:11]
	v_mfma_f32_16x16x32_bf16 v[44:47], v[136:139], v[168:171], v[44:47]
	v_mfma_f32_16x16x32_bf16 v[40:43], v[144:147], v[168:171], v[40:43]
	v_mfma_f32_16x16x32_bf16 v[32:35], v[136:139], v[180:183], v[32:35]
	v_mfma_f32_16x16x32_bf16 v[24:27], v[144:147], v[180:183], v[24:27]
	v_mfma_f32_16x16x32_bf16 v[16:19], v[136:139], v[188:191], v[16:19]
	v_mfma_f32_16x16x32_bf16 v[8:11], v[144:147], v[188:191], v[8:11]
	s_setprio 0
	s_setprio 1
	v_mfma_f32_16x16x32_bf16 v[36:39], v[148:151], v[164:167], v[36:39]
	v_mfma_f32_16x16x32_bf16 v[28:31], v[156:159], v[164:167], v[28:31]
	v_mfma_f32_16x16x32_bf16 v[20:23], v[148:151], v[176:179], v[20:23]
	v_mfma_f32_16x16x32_bf16 v[12:15], v[156:159], v[176:179], v[12:15]
	v_mfma_f32_16x16x32_bf16 v[4:7], v[148:151], v[184:187], v[4:7]
	v_mfma_f32_16x16x32_bf16 v[0:3], v[156:159], v[184:187], v[0:3]
	v_mfma_f32_16x16x32_bf16 v[36:39], v[152:155], v[168:171], v[36:39]
	v_mfma_f32_16x16x32_bf16 v[28:31], v[160:163], v[168:171], v[28:31]
	v_mfma_f32_16x16x32_bf16 v[20:23], v[152:155], v[180:183], v[20:23]
	v_mfma_f32_16x16x32_bf16 v[12:15], v[160:163], v[180:183], v[12:15]
	v_mfma_f32_16x16x32_bf16 v[4:7], v[152:155], v[188:191], v[4:7]
	v_mfma_f32_16x16x32_bf16 v[0:3], v[160:163], v[188:191], v[0:3]
	s_setprio 0
	s_cmp_gt_u32 s75, 13
	s_cbranch_scc1 .Lrot_x3
	s_mov_b32 s75, s22
	s_cmp_lg_u32 s75, 14
	s_cselect_b64 s[42:43], -1, 0
	s_or_b64 s[44:45], s[8:9], s[42:43]
	s_or_b64 s[44:45], s[44:45], s[10:11]
	s_and_b64 vcc, exec, s[44:45]
	s_barrier
	s_cbranch_vccnz .LBB0_2124
	s_branch .Lrot_a3
.Lrot_x3:
	s_mov_b32 s75, s22
	s_barrier
	s_branch .LBB0_2141

.Lrot_a3:
	s_and_saveexec_b64 s[44:45], s[4:5]
	s_cbranch_execz .LBB0_2123
	s_memrealtime s[46:47]
	s_mov_b32 s22, 1
	s_branch .LBB0_2130

.LBB0_3220:
	s_or_b32 s24, s84, 1
	ds_read_b128 v[112:115], v122
	ds_read_b128 v[138:141], v123
	ds_read_b128 v[142:145], v124
	ds_read_b128 v[146:149], v125
	ds_read_b128 v[150:153], v126
	ds_read_b128 v[154:157], v127
	ds_read_b128 v[158:161], v128
	ds_read_b128 v[162:165], v129
	s_lshl_b64 s[56:57], s[24:25], 7
	s_add_u32 s58, s36, s56
	s_addc_u32 s59, s37, s57
	s_add_i32 s24, s84, 2
	s_lshl_b64 s[66:67], s[24:25], 7
	s_add_u32 s68, s36, s66
	s_addc_u32 s69, s37, s67
	s_and_b64 s[56:57], s[52:53], exec
	s_cselect_b32 s57, s69, s45
	s_cselect_b32 s56, s68, s44
	s_add_u32 s66, s40, s66
	s_addc_u32 s67, s41, s67
	s_and_b64 s[52:53], s[52:53], exec
	s_cselect_b32 s53, s67, s15
	s_cselect_b32 s52, s66, s43
	s_mov_b32 m0, s79
	v_lshl_add_u64 v[116:117], s[58:59], 0, v[96:97]
	ds_read_b128 v[166:169], v120
	ds_read_b128 v[170:173], v120 offset:1024
	ds_read_b128 v[176:179], v120 offset:2048
	ds_read_b128 v[180:183], v120 offset:3072
	ds_read_b128 v[184:187], v120 offset:4096
	ds_read_b128 v[188:191], v120 offset:5120
	global_load_lds_dwordx4 v[116:117], off
	v_lshl_add_u64 v[116:117], s[58:59], 0, v[98:99]
	s_mov_b32 m0, s80
	s_nop 0
	global_load_lds_dwordx4 v[116:117], off
	v_lshl_add_u64 v[116:117], s[58:59], 0, v[100:101]
	s_mov_b32 m0, s81
	s_nop 0
	global_load_lds_dwordx4 v[116:117], off
	s_waitcnt lgkmcnt(6)
	s_barrier
	s_waitcnt lgkmcnt(0)
	s_setprio 1
	s_waitcnt lgkmcnt(0)
	v_mfma_f32_16x16x32_bf16 v[92:95], v[112:115], v[166:169], v[92:95]
	v_mfma_f32_16x16x32_bf16 v[88:91], v[142:145], v[166:169], v[88:91]
	v_mfma_f32_16x16x32_bf16 v[76:79], v[112:115], v[176:179], v[76:79]
	v_mfma_f32_16x16x32_bf16 v[72:75], v[142:145], v[176:179], v[72:75]
	v_mfma_f32_16x16x32_bf16 v[60:63], v[112:115], v[184:187], v[60:63]
	v_mfma_f32_16x16x32_bf16 v[56:59], v[142:145], v[184:187], v[56:59]
	v_mfma_f32_16x16x32_bf16 v[92:95], v[138:141], v[170:173], v[92:95]
	v_mfma_f32_16x16x32_bf16 v[88:91], v[146:149], v[170:173], v[88:91]
	v_mfma_f32_16x16x32_bf16 v[76:79], v[138:141], v[180:183], v[76:79]
	v_mfma_f32_16x16x32_bf16 v[72:75], v[146:149], v[180:183], v[72:75]
	v_mfma_f32_16x16x32_bf16 v[60:63], v[138:141], v[188:191], v[60:63]
	v_mfma_f32_16x16x32_bf16 v[56:59], v[146:149], v[188:191], v[56:59]
	s_setprio 0
	s_setprio 1
	v_mfma_f32_16x16x32_bf16 v[84:87], v[150:153], v[166:169], v[84:87]
	v_mfma_f32_16x16x32_bf16 v[80:83], v[158:161], v[166:169], v[80:83]
	v_mfma_f32_16x16x32_bf16 v[68:71], v[150:153], v[176:179], v[68:71]
	v_mfma_f32_16x16x32_bf16 v[64:67], v[158:161], v[176:179], v[64:67]
	v_mfma_f32_16x16x32_bf16 v[52:55], v[150:153], v[184:187], v[52:55]
	v_mfma_f32_16x16x32_bf16 v[48:51], v[158:161], v[184:187], v[48:51]
	v_mfma_f32_16x16x32_bf16 v[84:87], v[154:157], v[170:173], v[84:87]
	v_mfma_f32_16x16x32_bf16 v[80:83], v[162:165], v[170:173], v[80:83]
	v_mfma_f32_16x16x32_bf16 v[68:71], v[154:157], v[180:183], v[68:71]
	v_mfma_f32_16x16x32_bf16 v[64:67], v[162:165], v[180:183], v[64:67]
	v_mfma_f32_16x16x32_bf16 v[52:55], v[154:157], v[188:191], v[52:55]
	v_mfma_f32_16x16x32_bf16 v[48:51], v[162:165], v[188:191], v[48:51]
	s_setprio 0
	s_barrier
	s_mov_b32 m0, s62
	v_lshl_add_u64 v[116:117], s[52:53], 0, v[102:103]
	s_add_u32 s58, s52, 0x40000
	ds_read_b128 v[166:169], v120 offset:12288
	ds_read_b128 v[170:173], v120 offset:13312
	ds_read_b128 v[176:179], v120 offset:14336
	ds_read_b128 v[180:183], v120 offset:15360
	ds_read_b128 v[184:187], v120 offset:16384
	ds_read_b128 v[188:191], v120 offset:17408
	global_load_lds_dwordx4 v[116:117], off
	v_lshl_add_u64 v[192:193], s[52:53], 0, v[104:105]
	s_mov_b32 m0, s63
	s_addc_u32 s59, s53, 0
	global_load_lds_dwordx4 v[192:193], off
	v_lshl_add_u64 v[194:195], s[58:59], 0, v[102:103]
	s_mov_b32 m0, s64
	s_nop 0
	global_load_lds_dwordx4 v[194:195], off
	v_lshl_add_u64 v[194:195], s[58:59], 0, v[104:105]
	s_mov_b32 m0, s65
	s_nop 0
	global_load_lds_dwordx4 v[194:195], off
	s_waitcnt vmcnt(4)
	s_waitcnt lgkmcnt(0)
	s_barrier
	s_setprio 1
	s_waitcnt lgkmcnt(0)
	v_mfma_f32_16x16x32_bf16 v[44:47], v[112:115], v[166:169], v[44:47]
	v_mfma_f32_16x16x32_bf16 v[40:43], v[142:145], v[166:169], v[40:43]
	v_mfma_f32_16x16x32_bf16 v[28:31], v[112:115], v[176:179], v[28:31]
	v_mfma_f32_16x16x32_bf16 v[24:27], v[142:145], v[176:179], v[24:27]
	v_mfma_f32_16x16x32_bf16 v[12:15], v[112:115], v[184:187], v[12:15]
	v_mfma_f32_16x16x32_bf16 v[8:11], v[142:145], v[184:187], v[8:11]
	v_mfma_f32_16x16x32_bf16 v[44:47], v[138:141], v[170:173], v[44:47]
	v_mfma_f32_16x16x32_bf16 v[40:43], v[146:149], v[170:173], v[40:43]
	v_mfma_f32_16x16x32_bf16 v[28:31], v[138:141], v[180:183], v[28:31]
	v_mfma_f32_16x16x32_bf16 v[24:27], v[146:149], v[180:183], v[24:27]
	v_mfma_f32_16x16x32_bf16 v[12:15], v[138:141], v[188:191], v[12:15]
	v_mfma_f32_16x16x32_bf16 v[8:11], v[146:149], v[188:191], v[8:11]
	s_setprio 0
	s_setprio 1
	v_mfma_f32_16x16x32_bf16 v[36:39], v[150:153], v[166:169], v[36:39]
	v_mfma_f32_16x16x32_bf16 v[32:35], v[158:161], v[166:169], v[32:35]
	v_mfma_f32_16x16x32_bf16 v[20:23], v[150:153], v[176:179], v[20:23]
	v_mfma_f32_16x16x32_bf16 v[16:19], v[158:161], v[176:179], v[16:19]
	v_mfma_f32_16x16x32_bf16 v[4:7], v[150:153], v[184:187], v[4:7]
	v_mfma_f32_16x16x32_bf16 v[0:3], v[158:161], v[184:187], v[0:3]
	v_mfma_f32_16x16x32_bf16 v[36:39], v[154:157], v[170:173], v[36:39]
	v_mfma_f32_16x16x32_bf16 v[32:35], v[162:165], v[170:173], v[32:35]
	v_mfma_f32_16x16x32_bf16 v[20:23], v[154:157], v[180:183], v[20:23]
	v_mfma_f32_16x16x32_bf16 v[16:19], v[162:165], v[180:183], v[16:19]
	v_mfma_f32_16x16x32_bf16 v[4:7], v[154:157], v[188:191], v[4:7]
	v_mfma_f32_16x16x32_bf16 v[0:3], v[162:165], v[188:191], v[0:3]
	s_setprio 0
	s_barrier
	ds_read_b128 v[112:115], v130
	ds_read_b128 v[138:141], v131
	ds_read_b128 v[142:145], v132
	ds_read_b128 v[146:149], v133
	ds_read_b128 v[150:153], v134
	ds_read_b128 v[154:157], v135
	ds_read_b128 v[158:161], v136
	ds_read_b128 v[162:165], v137
	s_mov_b32 m0, s61
	v_lshl_add_u64 v[194:195], s[56:57], 0, v[96:97]
	ds_read_b128 v[166:169], v120 offset:32768
	ds_read_b128 v[170:173], v120 offset:33792
	ds_read_b128 v[176:179], v120 offset:34816
	ds_read_b128 v[180:183], v120 offset:35840
	ds_read_b128 v[184:187], v120 offset:36864
	ds_read_b128 v[188:191], v120 offset:37888
	global_load_lds_dwordx4 v[194:195], off
	v_lshl_add_u64 v[194:195], s[56:57], 0, v[98:99]
	s_mov_b32 m0, s70
	s_nop 0
	global_load_lds_dwordx4 v[194:195], off
	v_lshl_add_u64 v[194:195], s[56:57], 0, v[100:101]
	s_mov_b32 m0, s71
	s_nop 0
	global_load_lds_dwordx4 v[194:195], off
	s_waitcnt lgkmcnt(6)
	s_barrier
	s_waitcnt lgkmcnt(0)
	s_setprio 1
	s_waitcnt lgkmcnt(0)
	v_mfma_f32_16x16x32_bf16 v[92:95], v[112:115], v[166:169], v[92:95]
	v_mfma_f32_16x16x32_bf16 v[88:91], v[142:145], v[166:169], v[88:91]
	v_mfma_f32_16x16x32_bf16 v[76:79], v[112:115], v[176:179], v[76:79]
	v_mfma_f32_16x16x32_bf16 v[72:75], v[142:145], v[176:179], v[72:75]
	v_mfma_f32_16x16x32_bf16 v[60:63], v[112:115], v[184:187], v[60:63]
	v_mfma_f32_16x16x32_bf16 v[56:59], v[142:145], v[184:187], v[56:59]
	v_mfma_f32_16x16x32_bf16 v[92:95], v[138:141], v[170:173], v[92:95]
	v_mfma_f32_16x16x32_bf16 v[88:91], v[146:149], v[170:173], v[88:91]
	v_mfma_f32_16x16x32_bf16 v[76:79], v[138:141], v[180:183], v[76:79]
	v_mfma_f32_16x16x32_bf16 v[72:75], v[146:149], v[180:183], v[72:75]
	v_mfma_f32_16x16x32_bf16 v[60:63], v[138:141], v[188:191], v[60:63]
	v_mfma_f32_16x16x32_bf16 v[56:59], v[146:149], v[188:191], v[56:59]
	s_setprio 0
	s_setprio 1
	v_mfma_f32_16x16x32_bf16 v[84:87], v[150:153], v[166:169], v[84:87]
	v_mfma_f32_16x16x32_bf16 v[80:83], v[158:161], v[166:169], v[80:83]
	v_mfma_f32_16x16x32_bf16 v[68:71], v[150:153], v[176:179], v[68:71]
	v_mfma_f32_16x16x32_bf16 v[64:67], v[158:161], v[176:179], v[64:67]
	v_mfma_f32_16x16x32_bf16 v[52:55], v[150:153], v[184:187], v[52:55]
	v_mfma_f32_16x16x32_bf16 v[48:51], v[158:161], v[184:187], v[48:51]
	v_mfma_f32_16x16x32_bf16 v[84:87], v[154:157], v[170:173], v[84:87]
	v_mfma_f32_16x16x32_bf16 v[80:83], v[162:165], v[170:173], v[80:83]
	v_mfma_f32_16x16x32_bf16 v[68:71], v[154:157], v[180:183], v[68:71]
	v_mfma_f32_16x16x32_bf16 v[64:67], v[162:165], v[180:183], v[64:67]
	v_mfma_f32_16x16x32_bf16 v[52:55], v[154:157], v[188:191], v[52:55]
	v_mfma_f32_16x16x32_bf16 v[48:51], v[162:165], v[188:191], v[48:51]
	s_setprio 0
	s_barrier
	s_mov_b32 m0, s73
	v_lshl_add_u64 v[116:117], v[116:117], 0, s[22:23]
	s_add_u32 s52, s52, 0x40080
	ds_read_b128 v[166:169], v120 offset:45056
	ds_read_b128 v[170:173], v120 offset:46080
	ds_read_b128 v[176:179], v120 offset:47104
	ds_read_b128 v[180:183], v120 offset:48128
	ds_read_b128 v[184:187], v120 offset:49152
	ds_read_b128 v[188:191], v120 offset:50176
	global_load_lds_dwordx4 v[116:117], off
	v_lshl_add_u64 v[116:117], v[192:193], 0, s[22:23]
	s_mov_b32 m0, s74
	s_addc_u32 s53, s53, 0
	global_load_lds_dwordx4 v[116:117], off
	v_lshl_add_u64 v[116:117], s[52:53], 0, v[102:103]
	s_mov_b32 m0, s75
	s_nop 0
	global_load_lds_dwordx4 v[116:117], off
	v_lshl_add_u64 v[116:117], s[52:53], 0, v[104:105]
	s_mov_b32 m0, s76
	s_nop 0
	global_load_lds_dwordx4 v[116:117], off
	s_waitcnt vmcnt(4)
	s_waitcnt lgkmcnt(0)
	s_barrier
	s_setprio 1
	s_waitcnt lgkmcnt(0)
	v_mfma_f32_16x16x32_bf16 v[44:47], v[112:115], v[166:169], v[44:47]
	v_mfma_f32_16x16x32_bf16 v[40:43], v[142:145], v[166:169], v[40:43]
	v_mfma_f32_16x16x32_bf16 v[28:31], v[112:115], v[176:179], v[28:31]
	v_mfma_f32_16x16x32_bf16 v[24:27], v[142:145], v[176:179], v[24:27]
	v_mfma_f32_16x16x32_bf16 v[12:15], v[112:115], v[184:187], v[12:15]
	v_mfma_f32_16x16x32_bf16 v[8:11], v[142:145], v[184:187], v[8:11]
	v_mfma_f32_16x16x32_bf16 v[44:47], v[138:141], v[170:173], v[44:47]
	v_mfma_f32_16x16x32_bf16 v[40:43], v[146:149], v[170:173], v[40:43]
	v_mfma_f32_16x16x32_bf16 v[28:31], v[138:141], v[180:183], v[28:31]
	v_mfma_f32_16x16x32_bf16 v[24:27], v[146:149], v[180:183], v[24:27]
	v_mfma_f32_16x16x32_bf16 v[12:15], v[138:141], v[188:191], v[12:15]
	v_mfma_f32_16x16x32_bf16 v[8:11], v[146:149], v[188:191], v[8:11]
	s_setprio 0
	s_setprio 1
	v_mfma_f32_16x16x32_bf16 v[36:39], v[150:153], v[166:169], v[36:39]
	v_mfma_f32_16x16x32_bf16 v[32:35], v[158:161], v[166:169], v[32:35]
	v_mfma_f32_16x16x32_bf16 v[20:23], v[150:153], v[176:179], v[20:23]
	v_mfma_f32_16x16x32_bf16 v[16:19], v[158:161], v[176:179], v[16:19]
	v_mfma_f32_16x16x32_bf16 v[4:7], v[150:153], v[184:187], v[4:7]
	v_mfma_f32_16x16x32_bf16 v[0:3], v[158:161], v[184:187], v[0:3]
	v_mfma_f32_16x16x32_bf16 v[36:39], v[154:157], v[170:173], v[36:39]
	v_mfma_f32_16x16x32_bf16 v[32:35], v[162:165], v[170:173], v[32:35]
	v_mfma_f32_16x16x32_bf16 v[20:23], v[154:157], v[180:183], v[20:23]
	v_mfma_f32_16x16x32_bf16 v[16:19], v[162:165], v[180:183], v[16:19]
	v_mfma_f32_16x16x32_bf16 v[4:7], v[154:157], v[188:191], v[4:7]
	v_mfma_f32_16x16x32_bf16 v[0:3], v[162:165], v[188:191], v[0:3]
	s_setprio 0
	s_cmp_gt_u32 s84, 13
	s_cbranch_scc1 .Lrot_x4
	s_mov_b32 s84, s24
	s_cmp_lg_u32 s84, 14
	s_cselect_b64 s[52:53], -1, 0
	s_or_b64 s[56:57], s[8:9], s[52:53]
	s_or_b64 s[56:57], s[56:57], s[10:11]
	s_and_b64 vcc, exec, s[56:57]
	s_barrier
	s_cbranch_vccnz .LBB0_3220
	s_branch .Lrot_a4
.Lrot_x4:
	s_mov_b32 s84, s24
	s_barrier
	s_branch .LBB0_3237

.Lrot_a4:
	s_and_saveexec_b64 s[56:57], s[4:5]
	s_cbranch_execz .LBB0_3219
	s_memrealtime s[58:59]
	s_mov_b32 s24, 1
	s_branch .LBB0_3226

.LBB0_3368:
	s_or_b32 s20, s84, 1
	ds_read_b128 v[144:147], v154
	ds_read_b128 v[170:173], v155
	ds_read_b128 v[176:179], v156
	ds_read_b128 v[180:183], v157
	ds_read_b128 v[184:187], v158
	ds_read_b128 v[188:191], v159
	ds_read_b128 v[192:195], v160
	ds_read_b128 v[196:199], v161
	s_lshl_b64 s[56:57], s[20:21], 7
	s_add_u32 s58, s46, s56
	s_addc_u32 s59, s47, s57
	s_add_i32 s20, s84, 2
	s_lshl_b64 s[66:67], s[20:21], 7
	s_add_u32 s68, s46, s66
	s_addc_u32 s69, s47, s67
	s_and_b64 s[56:57], s[52:53], exec
	s_cselect_b32 s57, s69, s35
	s_cselect_b32 s56, s68, s43
	s_add_u32 s66, s48, s66
	s_addc_u32 s67, s49, s67
	s_and_b64 s[52:53], s[52:53], exec
	s_cselect_b32 s53, s67, s31
	s_cselect_b32 s52, s66, s83
	s_mov_b32 m0, s77
	v_lshl_add_u64 v[148:149], s[58:59], 0, v[128:129]
	ds_read_b128 v[200:203], v152
	ds_read_b128 v[204:207], v152 offset:1024
	ds_read_b128 v[208:211], v152 offset:2048
	ds_read_b128 v[212:215], v152 offset:3072
	ds_read_b128 v[216:219], v152 offset:4096
	ds_read_b128 v[220:223], v152 offset:5120
	ds_read_b128 v[224:227], v152 offset:6144
	ds_read_b128 v[228:231], v152 offset:7168
	global_load_lds_dwordx4 v[148:149], off
	v_lshl_add_u64 v[148:149], s[58:59], 0, v[130:131]
	s_mov_b32 m0, s78
	s_nop 0
	global_load_lds_dwordx4 v[148:149], off
	v_lshl_add_u64 v[148:149], s[58:59], 0, v[132:133]
	s_mov_b32 m0, s79
	s_nop 0
	global_load_lds_dwordx4 v[148:149], off
	v_lshl_add_u64 v[148:149], s[58:59], 0, v[134:135]
	s_mov_b32 m0, s80
	s_nop 0
	global_load_lds_dwordx4 v[148:149], off
	s_waitcnt lgkmcnt(8)
	s_barrier
	s_waitcnt lgkmcnt(0)
	s_setprio 1
	s_waitcnt lgkmcnt(0)
	v_mfma_f32_16x16x32_bf16 v[120:123], v[144:147], v[200:203], v[120:123]
	v_mfma_f32_16x16x32_bf16 v[124:127], v[176:179], v[200:203], v[124:127]
	v_mfma_f32_16x16x32_bf16 v[104:107], v[144:147], v[208:211], v[104:107]
	v_mfma_f32_16x16x32_bf16 v[108:111], v[176:179], v[208:211], v[108:111]
	v_mfma_f32_16x16x32_bf16 v[88:91], v[144:147], v[216:219], v[88:91]
	v_mfma_f32_16x16x32_bf16 v[92:95], v[176:179], v[216:219], v[92:95]
	v_mfma_f32_16x16x32_bf16 v[72:75], v[144:147], v[224:227], v[72:75]
	v_mfma_f32_16x16x32_bf16 v[76:79], v[176:179], v[224:227], v[76:79]
	v_mfma_f32_16x16x32_bf16 v[120:123], v[170:173], v[204:207], v[120:123]
	v_mfma_f32_16x16x32_bf16 v[124:127], v[180:183], v[204:207], v[124:127]
	v_mfma_f32_16x16x32_bf16 v[104:107], v[170:173], v[212:215], v[104:107]
	v_mfma_f32_16x16x32_bf16 v[108:111], v[180:183], v[212:215], v[108:111]
	v_mfma_f32_16x16x32_bf16 v[88:91], v[170:173], v[220:223], v[88:91]
	v_mfma_f32_16x16x32_bf16 v[92:95], v[180:183], v[220:223], v[92:95]
	v_mfma_f32_16x16x32_bf16 v[72:75], v[170:173], v[228:231], v[72:75]
	v_mfma_f32_16x16x32_bf16 v[76:79], v[180:183], v[228:231], v[76:79]
	s_setprio 0
	s_setprio 1
	v_mfma_f32_16x16x32_bf16 v[112:115], v[184:187], v[200:203], v[112:115]
	v_mfma_f32_16x16x32_bf16 v[116:119], v[192:195], v[200:203], v[116:119]
	v_mfma_f32_16x16x32_bf16 v[96:99], v[184:187], v[208:211], v[96:99]
	v_mfma_f32_16x16x32_bf16 v[100:103], v[192:195], v[208:211], v[100:103]
	v_mfma_f32_16x16x32_bf16 v[80:83], v[184:187], v[216:219], v[80:83]
	v_mfma_f32_16x16x32_bf16 v[84:87], v[192:195], v[216:219], v[84:87]
	v_mfma_f32_16x16x32_bf16 v[64:67], v[184:187], v[224:227], v[64:67]
	v_mfma_f32_16x16x32_bf16 v[68:71], v[192:195], v[224:227], v[68:71]
	v_mfma_f32_16x16x32_bf16 v[112:115], v[188:191], v[204:207], v[112:115]
	v_mfma_f32_16x16x32_bf16 v[116:119], v[196:199], v[204:207], v[116:119]
	v_mfma_f32_16x16x32_bf16 v[96:99], v[188:191], v[212:215], v[96:99]
	v_mfma_f32_16x16x32_bf16 v[100:103], v[196:199], v[212:215], v[100:103]
	v_mfma_f32_16x16x32_bf16 v[80:83], v[188:191], v[220:223], v[80:83]
	v_mfma_f32_16x16x32_bf16 v[84:87], v[196:199], v[220:223], v[84:87]
	v_mfma_f32_16x16x32_bf16 v[64:67], v[188:191], v[228:231], v[64:67]
	v_mfma_f32_16x16x32_bf16 v[68:71], v[196:199], v[228:231], v[68:71]
	s_setprio 0
	s_barrier
	s_mov_b32 m0, s60
	v_lshl_add_u64 v[148:149], s[52:53], 0, v[136:137]
	s_add_u32 s58, s52, 0x40000
	ds_read_b128 v[200:203], v152 offset:16384
	ds_read_b128 v[204:207], v152 offset:17408
	ds_read_b128 v[208:211], v152 offset:18432
	ds_read_b128 v[212:215], v152 offset:19456
	ds_read_b128 v[216:219], v152 offset:20480
	ds_read_b128 v[220:223], v152 offset:21504
	ds_read_b128 v[224:227], v152 offset:22528
	ds_read_b128 v[228:231], v152 offset:23552
	global_load_lds_dwordx4 v[148:149], off
	v_lshl_add_u64 v[232:233], s[52:53], 0, v[138:139]
	s_mov_b32 m0, s61
	s_addc_u32 s59, s53, 0
	global_load_lds_dwordx4 v[232:233], off
	v_lshl_add_u64 v[234:235], s[58:59], 0, v[136:137]
	s_mov_b32 m0, s62
	s_nop 0
	global_load_lds_dwordx4 v[234:235], off
	v_lshl_add_u64 v[234:235], s[58:59], 0, v[138:139]
	s_mov_b32 m0, s63
	s_nop 0
	global_load_lds_dwordx4 v[234:235], off
	s_waitcnt vmcnt(4)
	s_waitcnt lgkmcnt(0)
	s_barrier
	s_setprio 1
	s_waitcnt lgkmcnt(0)
	v_mfma_f32_16x16x32_bf16 v[56:59], v[144:147], v[200:203], v[56:59]
	v_mfma_f32_16x16x32_bf16 v[60:63], v[176:179], v[200:203], v[60:63]
	v_mfma_f32_16x16x32_bf16 v[40:43], v[144:147], v[208:211], v[40:43]
	v_mfma_f32_16x16x32_bf16 v[44:47], v[176:179], v[208:211], v[44:47]
	v_mfma_f32_16x16x32_bf16 v[24:27], v[144:147], v[216:219], v[24:27]
	v_mfma_f32_16x16x32_bf16 v[28:31], v[176:179], v[216:219], v[28:31]
	v_mfma_f32_16x16x32_bf16 v[8:11], v[144:147], v[224:227], v[8:11]
	v_mfma_f32_16x16x32_bf16 v[12:15], v[176:179], v[224:227], v[12:15]
	v_mfma_f32_16x16x32_bf16 v[56:59], v[170:173], v[204:207], v[56:59]
	v_mfma_f32_16x16x32_bf16 v[60:63], v[180:183], v[204:207], v[60:63]
	v_mfma_f32_16x16x32_bf16 v[40:43], v[170:173], v[212:215], v[40:43]
	v_mfma_f32_16x16x32_bf16 v[44:47], v[180:183], v[212:215], v[44:47]
	v_mfma_f32_16x16x32_bf16 v[24:27], v[170:173], v[220:223], v[24:27]
	v_mfma_f32_16x16x32_bf16 v[28:31], v[180:183], v[220:223], v[28:31]
	v_mfma_f32_16x16x32_bf16 v[8:11], v[170:173], v[228:231], v[8:11]
	v_mfma_f32_16x16x32_bf16 v[12:15], v[180:183], v[228:231], v[12:15]
	s_setprio 0
	s_setprio 1
	v_mfma_f32_16x16x32_bf16 v[48:51], v[184:187], v[200:203], v[48:51]
	v_mfma_f32_16x16x32_bf16 v[52:55], v[192:195], v[200:203], v[52:55]
	v_mfma_f32_16x16x32_bf16 v[32:35], v[184:187], v[208:211], v[32:35]
	v_mfma_f32_16x16x32_bf16 v[36:39], v[192:195], v[208:211], v[36:39]
	v_mfma_f32_16x16x32_bf16 v[16:19], v[184:187], v[216:219], v[16:19]
	v_mfma_f32_16x16x32_bf16 v[20:23], v[192:195], v[216:219], v[20:23]
	v_mfma_f32_16x16x32_bf16 v[0:3], v[184:187], v[224:227], v[0:3]
	v_mfma_f32_16x16x32_bf16 v[4:7], v[192:195], v[224:227], v[4:7]
	v_mfma_f32_16x16x32_bf16 v[48:51], v[188:191], v[204:207], v[48:51]
	v_mfma_f32_16x16x32_bf16 v[52:55], v[196:199], v[204:207], v[52:55]
	v_mfma_f32_16x16x32_bf16 v[32:35], v[188:191], v[212:215], v[32:35]
	v_mfma_f32_16x16x32_bf16 v[36:39], v[196:199], v[212:215], v[36:39]
	v_mfma_f32_16x16x32_bf16 v[16:19], v[188:191], v[220:223], v[16:19]
	v_mfma_f32_16x16x32_bf16 v[20:23], v[196:199], v[220:223], v[20:23]
	v_mfma_f32_16x16x32_bf16 v[0:3], v[188:191], v[228:231], v[0:3]
	v_mfma_f32_16x16x32_bf16 v[4:7], v[196:199], v[228:231], v[4:7]
	s_setprio 0
	s_barrier
	ds_read_b128 v[144:147], v162
	ds_read_b128 v[170:173], v163
	ds_read_b128 v[176:179], v164
	ds_read_b128 v[180:183], v165
	ds_read_b128 v[184:187], v166
	ds_read_b128 v[188:191], v167
	ds_read_b128 v[192:195], v168
	ds_read_b128 v[196:199], v169
	s_mov_b32 m0, s45
	v_lshl_add_u64 v[234:235], s[56:57], 0, v[128:129]
	ds_read_b128 v[200:203], v152 offset:32768
	ds_read_b128 v[204:207], v152 offset:33792
	ds_read_b128 v[208:211], v152 offset:34816
	ds_read_b128 v[212:215], v152 offset:35840
	ds_read_b128 v[216:219], v152 offset:36864
	ds_read_b128 v[220:223], v152 offset:37888
	ds_read_b128 v[224:227], v152 offset:38912
	ds_read_b128 v[228:231], v152 offset:39936
	global_load_lds_dwordx4 v[234:235], off
	v_lshl_add_u64 v[234:235], s[56:57], 0, v[130:131]
	s_mov_b32 m0, s64
	s_nop 0
	global_load_lds_dwordx4 v[234:235], off
	v_lshl_add_u64 v[234:235], s[56:57], 0, v[132:133]
	s_mov_b32 m0, s65
	s_nop 0
	global_load_lds_dwordx4 v[234:235], off
	v_lshl_add_u64 v[234:235], s[56:57], 0, v[134:135]
	s_mov_b32 m0, s70
	s_nop 0
	global_load_lds_dwordx4 v[234:235], off
	s_waitcnt lgkmcnt(8)
	s_barrier
	s_waitcnt lgkmcnt(0)
	s_setprio 1
	s_waitcnt lgkmcnt(0)
	v_mfma_f32_16x16x32_bf16 v[120:123], v[144:147], v[200:203], v[120:123]
	v_mfma_f32_16x16x32_bf16 v[124:127], v[176:179], v[200:203], v[124:127]
	v_mfma_f32_16x16x32_bf16 v[104:107], v[144:147], v[208:211], v[104:107]
	v_mfma_f32_16x16x32_bf16 v[108:111], v[176:179], v[208:211], v[108:111]
	v_mfma_f32_16x16x32_bf16 v[88:91], v[144:147], v[216:219], v[88:91]
	v_mfma_f32_16x16x32_bf16 v[92:95], v[176:179], v[216:219], v[92:95]
	v_mfma_f32_16x16x32_bf16 v[72:75], v[144:147], v[224:227], v[72:75]
	v_mfma_f32_16x16x32_bf16 v[76:79], v[176:179], v[224:227], v[76:79]
	v_mfma_f32_16x16x32_bf16 v[120:123], v[170:173], v[204:207], v[120:123]
	v_mfma_f32_16x16x32_bf16 v[124:127], v[180:183], v[204:207], v[124:127]
	v_mfma_f32_16x16x32_bf16 v[104:107], v[170:173], v[212:215], v[104:107]
	v_mfma_f32_16x16x32_bf16 v[108:111], v[180:183], v[212:215], v[108:111]
	v_mfma_f32_16x16x32_bf16 v[88:91], v[170:173], v[220:223], v[88:91]
	v_mfma_f32_16x16x32_bf16 v[92:95], v[180:183], v[220:223], v[92:95]
	v_mfma_f32_16x16x32_bf16 v[72:75], v[170:173], v[228:231], v[72:75]
	v_mfma_f32_16x16x32_bf16 v[76:79], v[180:183], v[228:231], v[76:79]
	s_setprio 0
	s_setprio 1
	v_mfma_f32_16x16x32_bf16 v[112:115], v[184:187], v[200:203], v[112:115]
	v_mfma_f32_16x16x32_bf16 v[116:119], v[192:195], v[200:203], v[116:119]
	v_mfma_f32_16x16x32_bf16 v[96:99], v[184:187], v[208:211], v[96:99]
	v_mfma_f32_16x16x32_bf16 v[100:103], v[192:195], v[208:211], v[100:103]
	v_mfma_f32_16x16x32_bf16 v[80:83], v[184:187], v[216:219], v[80:83]
	v_mfma_f32_16x16x32_bf16 v[84:87], v[192:195], v[216:219], v[84:87]
	v_mfma_f32_16x16x32_bf16 v[64:67], v[184:187], v[224:227], v[64:67]
	v_mfma_f32_16x16x32_bf16 v[68:71], v[192:195], v[224:227], v[68:71]
	v_mfma_f32_16x16x32_bf16 v[112:115], v[188:191], v[204:207], v[112:115]
	v_mfma_f32_16x16x32_bf16 v[116:119], v[196:199], v[204:207], v[116:119]
	v_mfma_f32_16x16x32_bf16 v[96:99], v[188:191], v[212:215], v[96:99]
	v_mfma_f32_16x16x32_bf16 v[100:103], v[196:199], v[212:215], v[100:103]
	v_mfma_f32_16x16x32_bf16 v[80:83], v[188:191], v[220:223], v[80:83]
	v_mfma_f32_16x16x32_bf16 v[84:87], v[196:199], v[220:223], v[84:87]
	v_mfma_f32_16x16x32_bf16 v[64:67], v[188:191], v[228:231], v[64:67]
	v_mfma_f32_16x16x32_bf16 v[68:71], v[196:199], v[228:231], v[68:71]
	s_setprio 0
	s_barrier
	s_mov_b32 m0, s71
	v_lshl_add_u64 v[148:149], v[148:149], 0, s[18:19]
	s_add_u32 s52, s52, 0x40080
	ds_read_b128 v[200:203], v152 offset:49152
	ds_read_b128 v[204:207], v152 offset:50176
	ds_read_b128 v[208:211], v152 offset:51200
	ds_read_b128 v[212:215], v152 offset:52224
	ds_read_b128 v[216:219], v152 offset:53248
	ds_read_b128 v[220:223], v152 offset:54272
	ds_read_b128 v[224:227], v152 offset:55296
	ds_read_b128 v[228:231], v152 offset:56320
	global_load_lds_dwordx4 v[148:149], off
	v_lshl_add_u64 v[148:149], v[232:233], 0, s[18:19]
	s_mov_b32 m0, s72
	s_addc_u32 s53, s53, 0
	global_load_lds_dwordx4 v[148:149], off
	v_lshl_add_u64 v[148:149], s[52:53], 0, v[136:137]
	s_mov_b32 m0, s73
	s_nop 0
	global_load_lds_dwordx4 v[148:149], off
	v_lshl_add_u64 v[148:149], s[52:53], 0, v[138:139]
	s_mov_b32 m0, s74
	s_nop 0
	global_load_lds_dwordx4 v[148:149], off
	s_waitcnt vmcnt(4)
	s_waitcnt lgkmcnt(0)
	s_barrier
	s_setprio 1
	s_waitcnt lgkmcnt(0)
	v_mfma_f32_16x16x32_bf16 v[56:59], v[144:147], v[200:203], v[56:59]
	v_mfma_f32_16x16x32_bf16 v[60:63], v[176:179], v[200:203], v[60:63]
	v_mfma_f32_16x16x32_bf16 v[40:43], v[144:147], v[208:211], v[40:43]
	v_mfma_f32_16x16x32_bf16 v[44:47], v[176:179], v[208:211], v[44:47]
	v_mfma_f32_16x16x32_bf16 v[24:27], v[144:147], v[216:219], v[24:27]
	v_mfma_f32_16x16x32_bf16 v[28:31], v[176:179], v[216:219], v[28:31]
	v_mfma_f32_16x16x32_bf16 v[8:11], v[144:147], v[224:227], v[8:11]
	v_mfma_f32_16x16x32_bf16 v[12:15], v[176:179], v[224:227], v[12:15]
	v_mfma_f32_16x16x32_bf16 v[56:59], v[170:173], v[204:207], v[56:59]
	v_mfma_f32_16x16x32_bf16 v[60:63], v[180:183], v[204:207], v[60:63]
	v_mfma_f32_16x16x32_bf16 v[40:43], v[170:173], v[212:215], v[40:43]
	v_mfma_f32_16x16x32_bf16 v[44:47], v[180:183], v[212:215], v[44:47]
	v_mfma_f32_16x16x32_bf16 v[24:27], v[170:173], v[220:223], v[24:27]
	v_mfma_f32_16x16x32_bf16 v[28:31], v[180:183], v[220:223], v[28:31]
	v_mfma_f32_16x16x32_bf16 v[8:11], v[170:173], v[228:231], v[8:11]
	v_mfma_f32_16x16x32_bf16 v[12:15], v[180:183], v[228:231], v[12:15]
	s_setprio 0
	s_setprio 1
	v_mfma_f32_16x16x32_bf16 v[48:51], v[184:187], v[200:203], v[48:51]
	v_mfma_f32_16x16x32_bf16 v[52:55], v[192:195], v[200:203], v[52:55]
	v_mfma_f32_16x16x32_bf16 v[32:35], v[184:187], v[208:211], v[32:35]
	v_mfma_f32_16x16x32_bf16 v[36:39], v[192:195], v[208:211], v[36:39]
	v_mfma_f32_16x16x32_bf16 v[16:19], v[184:187], v[216:219], v[16:19]
	v_mfma_f32_16x16x32_bf16 v[20:23], v[192:195], v[216:219], v[20:23]
	v_mfma_f32_16x16x32_bf16 v[0:3], v[184:187], v[224:227], v[0:3]
	v_mfma_f32_16x16x32_bf16 v[4:7], v[192:195], v[224:227], v[4:7]
	v_mfma_f32_16x16x32_bf16 v[48:51], v[188:191], v[204:207], v[48:51]
	v_mfma_f32_16x16x32_bf16 v[52:55], v[196:199], v[204:207], v[52:55]
	v_mfma_f32_16x16x32_bf16 v[32:35], v[188:191], v[212:215], v[32:35]
	v_mfma_f32_16x16x32_bf16 v[36:39], v[196:199], v[212:215], v[36:39]
	v_mfma_f32_16x16x32_bf16 v[16:19], v[188:191], v[220:223], v[16:19]
	v_mfma_f32_16x16x32_bf16 v[20:23], v[196:199], v[220:223], v[20:23]
	v_mfma_f32_16x16x32_bf16 v[0:3], v[188:191], v[228:231], v[0:3]
	v_mfma_f32_16x16x32_bf16 v[4:7], v[196:199], v[228:231], v[4:7]
	s_setprio 0
	s_cmp_gt_u32 s84, 13
	s_cbranch_scc1 .Lrot_x5
	s_mov_b32 s84, s20
	s_cmp_lg_u32 s84, 14
	s_cselect_b64 s[52:53], -1, 0
	s_or_b64 s[56:57], s[8:9], s[52:53]
	s_or_b64 s[56:57], s[56:57], s[10:11]
	s_and_b64 vcc, exec, s[56:57]
	s_barrier
	s_cbranch_vccnz .LBB0_3368
	s_branch .Lrot_a5

.LBB0_3483:
	ds_read_b128 v[142:145], v125
	ds_read_b128 v[146:149], v126
	ds_read_b128 v[150:153], v127
	ds_read_b128 v[154:157], v128
	ds_read_b128 v[158:161], v129
	ds_read_b128 v[162:165], v130
	ds_read_b128 v[166:169], v131
	ds_read_b128 v[170:173], v132
	s_add_u32 s34, s26, s6
	s_addc_u32 s35, s27, s7
	s_add_u32 s34, s34, 0x100
	s_addc_u32 s35, s35, 0
	s_add_u32 s65, s62, s6
	s_addc_u32 s66, s63, s7
	s_cmpk_eq_i32 s6, 0x1f00
	s_cselect_b32 s37, s29, s35
	s_cselect_b32 s36, s28, s34
	s_cselect_b32 s35, s13, s66
	s_cselect_b32 s34, s25, s65
	s_mov_b32 m0, s58
	v_lshl_add_u64 v[200:201], v[120:121], 0, s[6:7]
	ds_read_b128 v[176:179], v123
	ds_read_b128 v[180:183], v123 offset:1024
	ds_read_b128 v[184:187], v123 offset:2048
	ds_read_b128 v[188:191], v123 offset:3072
	ds_read_b128 v[192:195], v123 offset:4096
	ds_read_b128 v[196:199], v123 offset:5120
	global_load_lds_dwordx4 v[200:201], off
	v_lshl_add_u64 v[200:201], v[118:119], 0, s[6:7]
	s_mov_b32 m0, s59
	s_nop 0
	global_load_lds_dwordx4 v[200:201], off
	v_lshl_add_u64 v[200:201], v[116:117], 0, s[6:7]
	s_mov_b32 m0, s60
	s_nop 0
	global_load_lds_dwordx4 v[200:201], off
	s_waitcnt lgkmcnt(6)
	s_barrier
	s_waitcnt lgkmcnt(0)
	s_setprio 1
	s_waitcnt lgkmcnt(0)
	v_mfma_f32_16x16x32_bf16 v[92:95], v[142:145], v[176:179], v[92:95]
	v_mfma_f32_16x16x32_bf16 v[88:91], v[150:153], v[176:179], v[88:91]
	v_mfma_f32_16x16x32_bf16 v[76:79], v[142:145], v[184:187], v[76:79]
	v_mfma_f32_16x16x32_bf16 v[72:75], v[150:153], v[184:187], v[72:75]
	v_mfma_f32_16x16x32_bf16 v[60:63], v[142:145], v[192:195], v[60:63]
	v_mfma_f32_16x16x32_bf16 v[56:59], v[150:153], v[192:195], v[56:59]
	v_mfma_f32_16x16x32_bf16 v[92:95], v[146:149], v[180:183], v[92:95]
	v_mfma_f32_16x16x32_bf16 v[88:91], v[154:157], v[180:183], v[88:91]
	v_mfma_f32_16x16x32_bf16 v[76:79], v[146:149], v[188:191], v[76:79]
	v_mfma_f32_16x16x32_bf16 v[72:75], v[154:157], v[188:191], v[72:75]
	v_mfma_f32_16x16x32_bf16 v[60:63], v[146:149], v[196:199], v[60:63]
	v_mfma_f32_16x16x32_bf16 v[56:59], v[154:157], v[196:199], v[56:59]
	s_setprio 0
	s_setprio 1
	v_mfma_f32_16x16x32_bf16 v[84:87], v[158:161], v[176:179], v[84:87]
	v_mfma_f32_16x16x32_bf16 v[80:83], v[166:169], v[176:179], v[80:83]
	v_mfma_f32_16x16x32_bf16 v[68:71], v[158:161], v[184:187], v[68:71]
	v_mfma_f32_16x16x32_bf16 v[64:67], v[166:169], v[184:187], v[64:67]
	v_mfma_f32_16x16x32_bf16 v[52:55], v[158:161], v[192:195], v[52:55]
	v_mfma_f32_16x16x32_bf16 v[48:51], v[166:169], v[192:195], v[48:51]
	v_mfma_f32_16x16x32_bf16 v[84:87], v[162:165], v[180:183], v[84:87]
	v_mfma_f32_16x16x32_bf16 v[80:83], v[170:173], v[180:183], v[80:83]
	v_mfma_f32_16x16x32_bf16 v[68:71], v[162:165], v[188:191], v[68:71]
	v_mfma_f32_16x16x32_bf16 v[64:67], v[170:173], v[188:191], v[64:67]
	v_mfma_f32_16x16x32_bf16 v[52:55], v[162:165], v[196:199], v[52:55]
	v_mfma_f32_16x16x32_bf16 v[48:51], v[170:173], v[196:199], v[48:51]
	s_setprio 0
	s_barrier
	s_mov_b32 m0, s43
	v_lshl_add_u64 v[200:201], s[34:35], 0, v[102:103]
	s_add_u32 s66, s34, 0x100000
	ds_read_b128 v[176:179], v123 offset:12288
	ds_read_b128 v[180:183], v123 offset:13312
	ds_read_b128 v[184:187], v123 offset:14336
	ds_read_b128 v[188:191], v123 offset:15360
	ds_read_b128 v[192:195], v123 offset:16384
	ds_read_b128 v[196:199], v123 offset:17408
	global_load_lds_dwordx4 v[200:201], off
	v_lshl_add_u64 v[202:203], s[34:35], 0, v[104:105]
	s_mov_b32 m0, s44
	s_addc_u32 s67, s35, 0
	global_load_lds_dwordx4 v[202:203], off
	v_lshl_add_u64 v[204:205], s[66:67], 0, v[102:103]
	s_mov_b32 m0, s45
	s_nop 0
	global_load_lds_dwordx4 v[204:205], off
	v_lshl_add_u64 v[204:205], s[66:67], 0, v[104:105]
	s_mov_b32 m0, s46
	s_nop 0
	global_load_lds_dwordx4 v[204:205], off
	s_waitcnt vmcnt(4)
	s_waitcnt lgkmcnt(0)
	s_barrier
	s_setprio 1
	s_waitcnt lgkmcnt(0)
	v_mfma_f32_16x16x32_bf16 v[44:47], v[142:145], v[176:179], v[44:47]
	v_mfma_f32_16x16x32_bf16 v[40:43], v[150:153], v[176:179], v[40:43]
	v_mfma_f32_16x16x32_bf16 v[28:31], v[142:145], v[184:187], v[28:31]
	v_mfma_f32_16x16x32_bf16 v[24:27], v[150:153], v[184:187], v[24:27]
	v_mfma_f32_16x16x32_bf16 v[12:15], v[142:145], v[192:195], v[12:15]
	v_mfma_f32_16x16x32_bf16 v[8:11], v[150:153], v[192:195], v[8:11]
	v_mfma_f32_16x16x32_bf16 v[44:47], v[146:149], v[180:183], v[44:47]
	v_mfma_f32_16x16x32_bf16 v[40:43], v[154:157], v[180:183], v[40:43]
	v_mfma_f32_16x16x32_bf16 v[28:31], v[146:149], v[188:191], v[28:31]
	v_mfma_f32_16x16x32_bf16 v[24:27], v[154:157], v[188:191], v[24:27]
	v_mfma_f32_16x16x32_bf16 v[12:15], v[146:149], v[196:199], v[12:15]
	v_mfma_f32_16x16x32_bf16 v[8:11], v[154:157], v[196:199], v[8:11]
	s_setprio 0
	s_setprio 1
	v_mfma_f32_16x16x32_bf16 v[36:39], v[158:161], v[176:179], v[36:39]
	v_mfma_f32_16x16x32_bf16 v[32:35], v[166:169], v[176:179], v[32:35]
	v_mfma_f32_16x16x32_bf16 v[20:23], v[158:161], v[184:187], v[20:23]
	v_mfma_f32_16x16x32_bf16 v[16:19], v[166:169], v[184:187], v[16:19]
	v_mfma_f32_16x16x32_bf16 v[4:7], v[158:161], v[192:195], v[4:7]
	v_mfma_f32_16x16x32_bf16 v[0:3], v[166:169], v[192:195], v[0:3]
	v_mfma_f32_16x16x32_bf16 v[36:39], v[162:165], v[180:183], v[36:39]
	v_mfma_f32_16x16x32_bf16 v[32:35], v[170:173], v[180:183], v[32:35]
	v_mfma_f32_16x16x32_bf16 v[20:23], v[162:165], v[188:191], v[20:23]
	v_mfma_f32_16x16x32_bf16 v[16:19], v[170:173], v[188:191], v[16:19]
	v_mfma_f32_16x16x32_bf16 v[4:7], v[162:165], v[196:199], v[4:7]
	v_mfma_f32_16x16x32_bf16 v[0:3], v[170:173], v[196:199], v[0:3]
	s_setprio 0
	s_barrier
	ds_read_b128 v[142:145], v133
	ds_read_b128 v[146:149], v134
	ds_read_b128 v[150:153], v135
	ds_read_b128 v[154:157], v136
	ds_read_b128 v[158:161], v137
	ds_read_b128 v[162:165], v138
	ds_read_b128 v[166:169], v139
	ds_read_b128 v[170:173], v140
	s_mov_b32 m0, s42
	v_lshl_add_u64 v[204:205], s[36:37], 0, v[96:97]
	ds_read_b128 v[176:179], v123 offset:32768
	ds_read_b128 v[180:183], v123 offset:33792
	ds_read_b128 v[184:187], v123 offset:34816
	ds_read_b128 v[188:191], v123 offset:35840
	ds_read_b128 v[192:195], v123 offset:36864
	ds_read_b128 v[196:199], v123 offset:37888
	global_load_lds_dwordx4 v[204:205], off
	v_lshl_add_u64 v[204:205], s[36:37], 0, v[98:99]
	s_mov_b32 m0, s47
	s_nop 0
	global_load_lds_dwordx4 v[204:205], off
	v_lshl_add_u64 v[204:205], s[36:37], 0, v[100:101]
	s_mov_b32 m0, s48
	s_nop 0
	global_load_lds_dwordx4 v[204:205], off
	s_waitcnt lgkmcnt(6)
	s_barrier
	s_waitcnt lgkmcnt(0)
	s_setprio 1
	s_waitcnt lgkmcnt(0)
	v_mfma_f32_16x16x32_bf16 v[92:95], v[142:145], v[176:179], v[92:95]
	v_mfma_f32_16x16x32_bf16 v[88:91], v[150:153], v[176:179], v[88:91]
	v_mfma_f32_16x16x32_bf16 v[76:79], v[142:145], v[184:187], v[76:79]
	v_mfma_f32_16x16x32_bf16 v[72:75], v[150:153], v[184:187], v[72:75]
	v_mfma_f32_16x16x32_bf16 v[60:63], v[142:145], v[192:195], v[60:63]
	v_mfma_f32_16x16x32_bf16 v[56:59], v[150:153], v[192:195], v[56:59]
	v_mfma_f32_16x16x32_bf16 v[92:95], v[146:149], v[180:183], v[92:95]
	v_mfma_f32_16x16x32_bf16 v[88:91], v[154:157], v[180:183], v[88:91]
	v_mfma_f32_16x16x32_bf16 v[76:79], v[146:149], v[188:191], v[76:79]
	v_mfma_f32_16x16x32_bf16 v[72:75], v[154:157], v[188:191], v[72:75]
	v_mfma_f32_16x16x32_bf16 v[60:63], v[146:149], v[196:199], v[60:63]
	v_mfma_f32_16x16x32_bf16 v[56:59], v[154:157], v[196:199], v[56:59]
	s_setprio 0
	s_setprio 1
	v_mfma_f32_16x16x32_bf16 v[84:87], v[158:161], v[176:179], v[84:87]
	v_mfma_f32_16x16x32_bf16 v[80:83], v[166:169], v[176:179], v[80:83]
	v_mfma_f32_16x16x32_bf16 v[68:71], v[158:161], v[184:187], v[68:71]
	v_mfma_f32_16x16x32_bf16 v[64:67], v[166:169], v[184:187], v[64:67]
	v_mfma_f32_16x16x32_bf16 v[52:55], v[158:161], v[192:195], v[52:55]
	v_mfma_f32_16x16x32_bf16 v[48:51], v[166:169], v[192:195], v[48:51]
	v_mfma_f32_16x16x32_bf16 v[84:87], v[162:165], v[180:183], v[84:87]
	v_mfma_f32_16x16x32_bf16 v[80:83], v[170:173], v[180:183], v[80:83]
	v_mfma_f32_16x16x32_bf16 v[68:71], v[162:165], v[188:191], v[68:71]
	v_mfma_f32_16x16x32_bf16 v[64:67], v[170:173], v[188:191], v[64:67]
	v_mfma_f32_16x16x32_bf16 v[52:55], v[162:165], v[196:199], v[52:55]
	v_mfma_f32_16x16x32_bf16 v[48:51], v[170:173], v[196:199], v[48:51]
	s_setprio 0
	s_barrier
	s_mov_b32 m0, s50
	v_lshl_add_u64 v[200:201], v[200:201], 0, s[10:11]
	s_add_u32 s34, s34, 0x100080
	ds_read_b128 v[176:179], v123 offset:45056
	ds_read_b128 v[180:183], v123 offset:46080
	ds_read_b128 v[184:187], v123 offset:47104
	ds_read_b128 v[188:191], v123 offset:48128
	ds_read_b128 v[192:195], v123 offset:49152
	ds_read_b128 v[196:199], v123 offset:50176
	global_load_lds_dwordx4 v[200:201], off
	v_lshl_add_u64 v[200:201], v[202:203], 0, s[10:11]
	s_mov_b32 m0, s51
	s_addc_u32 s35, s35, 0
	global_load_lds_dwordx4 v[200:201], off
	v_lshl_add_u64 v[200:201], s[34:35], 0, v[102:103]
	s_mov_b32 m0, s52
	s_nop 0
	global_load_lds_dwordx4 v[200:201], off
	v_lshl_add_u64 v[200:201], s[34:35], 0, v[104:105]
	s_mov_b32 m0, s53
	s_nop 0
	global_load_lds_dwordx4 v[200:201], off
	s_waitcnt vmcnt(4)
	s_waitcnt lgkmcnt(0)
	s_barrier
	s_setprio 1
	s_waitcnt lgkmcnt(0)
	v_mfma_f32_16x16x32_bf16 v[44:47], v[142:145], v[176:179], v[44:47]
	v_mfma_f32_16x16x32_bf16 v[40:43], v[150:153], v[176:179], v[40:43]
	v_mfma_f32_16x16x32_bf16 v[28:31], v[142:145], v[184:187], v[28:31]
	v_mfma_f32_16x16x32_bf16 v[24:27], v[150:153], v[184:187], v[24:27]
	v_mfma_f32_16x16x32_bf16 v[12:15], v[142:145], v[192:195], v[12:15]
	v_mfma_f32_16x16x32_bf16 v[8:11], v[150:153], v[192:195], v[8:11]
	v_mfma_f32_16x16x32_bf16 v[44:47], v[146:149], v[180:183], v[44:47]
	v_mfma_f32_16x16x32_bf16 v[40:43], v[154:157], v[180:183], v[40:43]
	v_mfma_f32_16x16x32_bf16 v[28:31], v[146:149], v[188:191], v[28:31]
	v_mfma_f32_16x16x32_bf16 v[24:27], v[154:157], v[188:191], v[24:27]
	v_mfma_f32_16x16x32_bf16 v[12:15], v[146:149], v[196:199], v[12:15]
	v_mfma_f32_16x16x32_bf16 v[8:11], v[154:157], v[196:199], v[8:11]
	s_setprio 0
	s_setprio 1
	v_mfma_f32_16x16x32_bf16 v[36:39], v[158:161], v[176:179], v[36:39]
	v_mfma_f32_16x16x32_bf16 v[32:35], v[166:169], v[176:179], v[32:35]
	v_mfma_f32_16x16x32_bf16 v[20:23], v[158:161], v[184:187], v[20:23]
	v_mfma_f32_16x16x32_bf16 v[16:19], v[166:169], v[184:187], v[16:19]
	v_mfma_f32_16x16x32_bf16 v[4:7], v[158:161], v[192:195], v[4:7]
	v_mfma_f32_16x16x32_bf16 v[0:3], v[166:169], v[192:195], v[0:3]
	v_mfma_f32_16x16x32_bf16 v[36:39], v[162:165], v[180:183], v[36:39]
	v_mfma_f32_16x16x32_bf16 v[32:35], v[170:173], v[180:183], v[32:35]
	v_mfma_f32_16x16x32_bf16 v[20:23], v[162:165], v[188:191], v[20:23]
	v_mfma_f32_16x16x32_bf16 v[16:19], v[170:173], v[188:191], v[16:19]
	v_mfma_f32_16x16x32_bf16 v[4:7], v[162:165], v[196:199], v[4:7]
	v_mfma_f32_16x16x32_bf16 v[0:3], v[170:173], v[196:199], v[0:3]
	s_setprio 0
	s_add_i32 s64, s64, 2
	s_add_u32 s6, s6, 0x100
	s_addc_u32 s7, s7, 0
	s_cmp_gt_u32 s64, 61
	s_barrier
	s_cbranch_scc0 .LBB0_3483
	s_mul_i32 s6, s56, 0xc0
	v_add_u32_e32 v118, s6, v122
	v_ashrrev_i32_e32 v119, 31, v118
	v_lshl_or_b32 v116, s12, 8, v124
	v_lshlrev_b64 v[120:121], 11, v[118:119]
	v_ashrrev_i32_e32 v117, 31, v116
	v_lshl_add_u64 v[120:121], s[8:9], 0, v[120:121]
	v_lshl_add_u64 v[120:121], v[116:117], 1, v[120:121]
	v_cmp_gt_i32_e32 vcc, s49, v116
	s_and_saveexec_b64 s[6:7], vcc
	s_cbranch_execz .LBB0_3486
	v_cvt_pk_bf16_f32 v92, v92, v93
	v_cvt_pk_bf16_f32 v93, v94, v95
	v_cvt_pk_bf16_f32 v94, v88, v89
	v_cvt_pk_bf16_f32 v95, v90, v91
	flat_store_dwordx4 v[120:121], v[92:95]
